# H1 + peeled first K-iteration with SrcC=0 (accumulator zeroing pass and its vmcnt(0) removed)
# speedup vs baseline: 1.0421x; 1.0005x over previous
; #define PG8_STAGE(bufoff, gbase, voff) do { _Pragma("unroll") for (int _i = 0; _i < 2; ++_i) \
;         __builtin_amdgcn_global_load_lds((const unsigned*)((const char*)(gbase) + (voff)[_i]), (PG8_LAS unsigned*)(lds + (bufoff) + ldsw + _i * 8192), 16, 0, 0); } while (0)
; #define PG8_WAIT_V(n) asm volatile("s_waitcnt vmcnt(" #n ")" ::: "memory")
; template <class Epi, class Sched>
; __device__ __forceinline__ void gemm_phase(PG8_LAS unsigned char* lds, const Gemm g, const Sched& S, const Epi& E) {
;     ...
;     for (;;) {
;         const bool has_next = S.next(ui + 1, nxt);
;         const char* nA = has_next ? (const char*)g.A + (size_t)nxt.pm * tstep : cA; const char* nB = has_next ? (const char*)g.Bt + (size_t)nxt.pn * tstep : cB;
;         for (int t = 0; t < nt; t += 2) {
;             const bool last = (t == nt - 2);
;             const char* a1 = cA + (size_t)(t + 1) * kstep;
;             const char* a2 = last ? nA : cA + (size_t)(t + 2) * kstep; const char* b2 = last ? nB : cB + (size_t)(t + 2) * kstep;
;             const char* a3 = a2 + kstep; const char* b3 = b2 + kstep;
;             if (last && has_next) S.a_ready(nxt);
;             PG8_LDB(B0, 0, 0); PG8_SCHED; PG8_LDA(At, 0, 0); PG8_STAGE(PG8_SA(1, 1), a1 + hstep, voffA);
;             PG8_WAIT_L(8); PG8_BAR; PG8_WAIT_L(0); PG8_MMA(0, 0, At, B0); PG8_BAR; PG8_SCHED;
;             PG8_LDB(B1, 0, 1); PG8_STAGE(PG8_SB(0, 0), b2, voffB);
;             PG8_BAR; PG8_WAIT_L(0); PG8_MMA(0, 1, At, B1); PG8_BAR;
;             PG8_LDA(At, 0, 1); PG8_STAGE(PG8_SA(0, 0), a2, voffA);
;             PG8_BAR; PG8_WAIT_L(0); PG8_MMA(1, 0, At, B0); PG8_BAR; PG8_SCHED;
;             PG8_STAGE(PG8_SB(0, 1), b2 + hstep, voffB);
;             PG8_WAIT_V(6); PG8_BAR; PG8_MMA(1, 1, At, B1); PG8_BAR;
;             PG8_LDB(B0, 1, 0); PG8_SCHED; PG8_LDA(At, 1, 0); PG8_STAGE(PG8_SA(0, 1), a2 + hstep, voffA);
;             PG8_WAIT_L(8); PG8_BAR; PG8_WAIT_L(0); PG8_MMA(0, 0, At, B0); PG8_BAR; PG8_SCHED;
;             PG8_LDB(B1, 1, 1); PG8_STAGE(PG8_SB(1, 0), b3, voffB);
;             PG8_BAR; PG8_WAIT_L(0); PG8_MMA(0, 1, At, B1); PG8_BAR;
;             PG8_LDA(At, 1, 1); PG8_STAGE(PG8_SA(1, 0), a3, voffA);
;             PG8_BAR; PG8_WAIT_L(0); PG8_MMA(1, 0, At, B0); PG8_BAR; PG8_SCHED;
;             PG8_STAGE(PG8_SB(1, 1), b3 + hstep, voffB);
;             PG8_WAIT_V(6); PG8_BAR; PG8_MMA(1, 1, At, B1); PG8_BAR;
.LBB0_234:
	s_ashr_i32 s49, s48, 31
	v_cmp_lt_i64_e32 vcc, s[50:51], v[152:153]
	s_lshl_b64 s[50:51], s[48:49], 20
	s_add_u32 s50, s76, s50
	s_addc_u32 s51, s77, s51
	s_and_b64 s[64:65], vcc, exec
	s_cselect_b32 s0, s51, s69
	s_cselect_b32 s5, s50, s68
	s_ashr_i32 s47, s46, 31
	s_lshl_b64 s[64:65], s[46:47], 20
	s_add_u32 s64, s58, s64
	s_addc_u32 s65, s59, s65
	s_and_b64 s[72:73], vcc, exec
	s_cselect_b32 s47, s65, s71
	s_cselect_b32 s49, s64, s70
	s_add_u32 s68, s68, 0x80080
	s_addc_u32 s69, s69, 0
	s_add_u32 s97, s70, 0x100
	s_addc_u32 vcc_lo, s71, 0
	s_mov_b32 vcc_hi, -2
	s_setprio 0
	ds_read_b128 v[128:131], v162
	ds_read_b128 v[132:135], v162 offset:1024
	ds_read_b128 v[154:157], v162 offset:2048
	ds_read_b128 v[166:169], v162 offset:3072
	ds_read_b128 v[170:173], v163
	ds_read_b128 v[174:177], v163 offset:1024
	ds_read_b128 v[178:181], v163 offset:2048
	ds_read_b128 v[182:185], v163 offset:3072
	ds_read_b128 v[186:189], v163 offset:4096
	ds_read_b128 v[190:193], v163 offset:5120
	ds_read_b128 v[194:197], v163 offset:6144
	ds_read_b128 v[198:201], v163 offset:7168
	ds_read_b128 v[202:205], v164
	ds_read_b128 v[206:209], v164 offset:1024
	ds_read_b128 v[210:213], v164 offset:2048
	ds_read_b128 v[214:217], v164 offset:3072
	s_add_u32 s10, s68, 0xfff80080
	s_addc_u32 s11, s69, -1
	s_cmp_eq_u32 vcc_hi, 28
	s_cselect_b32 s73, s0, s11
	s_cselect_b32 s72, s5, s10
	s_cselect_b32 s71, s47, vcc_lo
	s_cselect_b32 s70, s49, s97
	v_lshl_add_u64 v[158:159], s[68:69], 0, v[148:149]
	s_add_i32 m0, s67, 0xc000
	s_nop 0
	global_load_lds_dwordx4 v[158:159], off
	v_lshl_add_u64 v[158:159], s[68:69], 0, v[150:151]
	s_add_i32 m0, s67, 0xe000
	s_nop 0
	global_load_lds_dwordx4 v[158:159], off
	s_waitcnt vmcnt(8)
	s_waitcnt lgkmcnt(0)
	s_setprio 1
	s_barrier
	v_mfma_f32_16x16x32_bf16 v[124:127], v[128:131], v[170:173], 0
	v_mfma_f32_16x16x32_bf16 v[120:123], v[154:157], v[170:173], 0
	v_mfma_f32_16x16x32_bf16 v[116:119], v[128:131], v[178:181], 0
	v_mfma_f32_16x16x32_bf16 v[112:115], v[154:157], v[178:181], 0
	v_mfma_f32_16x16x32_bf16 v[108:111], v[128:131], v[186:189], 0
	v_mfma_f32_16x16x32_bf16 v[104:107], v[154:157], v[186:189], 0
	v_mfma_f32_16x16x32_bf16 v[100:103], v[128:131], v[194:197], 0
	v_mfma_f32_16x16x32_bf16 v[96:99], v[154:157], v[194:197], 0
	v_mfma_f32_16x16x32_bf16 v[124:127], v[132:135], v[174:177], v[124:127]
	v_mfma_f32_16x16x32_bf16 v[120:123], v[166:169], v[174:177], v[120:123]
	v_mfma_f32_16x16x32_bf16 v[116:119], v[132:135], v[182:185], v[116:119]
	v_mfma_f32_16x16x32_bf16 v[112:115], v[166:169], v[182:185], v[112:115]
	v_mfma_f32_16x16x32_bf16 v[108:111], v[132:135], v[190:193], v[108:111]
	v_mfma_f32_16x16x32_bf16 v[104:107], v[166:169], v[190:193], v[104:107]
	v_mfma_f32_16x16x32_bf16 v[100:103], v[132:135], v[198:201], v[100:103]
	v_mfma_f32_16x16x32_bf16 v[96:99], v[166:169], v[198:201], v[96:99]
	v_mfma_f32_16x16x32_bf16 v[60:63], v[202:205], v[170:173], 0
	v_mfma_f32_16x16x32_bf16 v[56:59], v[210:213], v[170:173], 0
	v_mfma_f32_16x16x32_bf16 v[52:55], v[202:205], v[178:181], 0
	v_mfma_f32_16x16x32_bf16 v[48:51], v[210:213], v[178:181], 0
	v_mfma_f32_16x16x32_bf16 v[44:47], v[202:205], v[186:189], 0
	v_mfma_f32_16x16x32_bf16 v[40:43], v[210:213], v[186:189], 0
	v_mfma_f32_16x16x32_bf16 v[36:39], v[202:205], v[194:197], 0
	v_mfma_f32_16x16x32_bf16 v[32:35], v[210:213], v[194:197], 0
	v_mfma_f32_16x16x32_bf16 v[60:63], v[206:209], v[174:177], v[60:63]
	v_mfma_f32_16x16x32_bf16 v[56:59], v[214:217], v[174:177], v[56:59]
	v_mfma_f32_16x16x32_bf16 v[52:55], v[206:209], v[182:185], v[52:55]
	v_mfma_f32_16x16x32_bf16 v[48:51], v[214:217], v[182:185], v[48:51]
	v_mfma_f32_16x16x32_bf16 v[44:47], v[206:209], v[190:193], v[44:47]
	v_mfma_f32_16x16x32_bf16 v[40:43], v[214:217], v[190:193], v[40:43]
	v_mfma_f32_16x16x32_bf16 v[36:39], v[206:209], v[198:201], v[36:39]
	v_mfma_f32_16x16x32_bf16 v[32:35], v[214:217], v[198:201], v[32:35]
	s_barrier
	s_setprio 0
	ds_read_b128 v[170:173], v163 offset:16384
	ds_read_b128 v[174:177], v163 offset:17408
	ds_read_b128 v[178:181], v163 offset:18432
	ds_read_b128 v[182:185], v163 offset:19456
	ds_read_b128 v[186:189], v163 offset:20480
	ds_read_b128 v[190:193], v163 offset:21504
	ds_read_b128 v[194:197], v163 offset:22528
	ds_read_b128 v[198:201], v163 offset:23552
	s_add_i32 s10, s90, s78
	v_lshl_add_u64 v[158:159], s[70:71], 0, v[138:139]
	s_mov_b32 m0, s10
	s_nop 0
	global_load_lds_dwordx4 v[158:159], off
	v_lshl_add_u64 v[218:219], s[70:71], 0, v[142:143]
	s_add_i32 m0, s10, 0x2000
	s_nop 0
	global_load_lds_dwordx4 v[218:219], off
	s_mov_b32 m0, s67
	v_lshl_add_u64 v[220:221], s[72:73], 0, v[136:137]
	global_load_lds_dwordx4 v[220:221], off
	v_lshl_add_u64 v[222:223], s[72:73], 0, v[140:141]
	s_mov_b32 m0, s79
	s_nop 0
	global_load_lds_dwordx4 v[222:223], off
	s_add_u32 s10, s70, 0x80000
	s_addc_u32 s11, s71, 0
	s_add_i32 s33, s91, s78
	v_lshl_add_u64 v[224:225], s[10:11], 0, v[138:139]
	s_mov_b32 m0, s33
	s_nop 0
	global_load_lds_dwordx4 v[224:225], off
	v_lshl_add_u64 v[224:225], s[10:11], 0, v[142:143]
	s_add_i32 m0, s33, 0x2000
	s_nop 0
	global_load_lds_dwordx4 v[224:225], off
	s_waitcnt vmcnt(8)
	s_waitcnt lgkmcnt(0)
	s_setprio 1
	s_barrier
; #define PG8_STAGE(bufoff, gbase, voff) do { _Pragma("unroll") for (int _i = 0; _i < 2; ++_i) \
;         __builtin_amdgcn_global_load_lds((const unsigned*)((const char*)(gbase) + (voff)[_i]), (PG8_LAS unsigned*)(lds + (bufoff) + ldsw + _i * 8192), 16, 0, 0); } while (0)
; #define PG8_LDA(dst, b, h) do { _Pragma("unroll") for (int m = 0; m < 4; ++m) _Pragma("unroll") for (int k = 0; k < 2; ++k) dst[m][k] = *(const PG8_LAS bf16x8*)(lds + PG8_SA(b, h) + aoff + m * 2048 + k * 1024); } while (0)
; #define PG8_LDB(dst, b, h) do { _Pragma("unroll") for (int n = 0; n < 2; ++n) _Pragma("unroll") for (int k = 0; k < 2; ++k) dst[n][k] = *(const PG8_LAS bf16x8*)(lds + PG8_SB(b, h) + boff + n * 2048 + k * 1024); } while (0)
; #define PG8_WAIT_V(n) asm volatile("s_waitcnt vmcnt(" #n ")" ::: "memory")
; #define PG8_WAIT_L(n) asm volatile("s_waitcnt lgkmcnt(" #n ")" ::: "memory")
; #define PG8_BAR __builtin_amdgcn_s_barrier()
; #define PG8_SCHED __builtin_amdgcn_sched_barrier(0)
; template <class Epi, class Sched>
; __device__ __forceinline__ void gemm_phase(PG8_LAS unsigned char* lds, const Gemm g, const Sched& S, const Epi& E) {
;     ...
;             PG8_LDB(B0, 0, 0); PG8_SCHED; PG8_LDA(At, 0, 0); PG8_STAGE(PG8_SA(1, 1), a1 + hstep, voffA);
;             PG8_WAIT_L(8); PG8_BAR; PG8_WAIT_L(0); PG8_MMA(0, 0, At, B0); PG8_BAR; PG8_SCHED;
;             PG8_LDB(B1, 0, 1); PG8_STAGE(PG8_SB(0, 0), b2, voffB);
;             PG8_BAR; PG8_WAIT_L(0); PG8_MMA(0, 1, At, B1); PG8_BAR;
;             PG8_LDA(At, 0, 1); PG8_STAGE(PG8_SA(0, 0), a2, voffA);
;             PG8_BAR; PG8_WAIT_L(0); PG8_MMA(1, 0, At, B0); PG8_BAR; PG8_SCHED;
;             PG8_STAGE(PG8_SB(0, 1), b2 + hstep, voffB);
;             PG8_WAIT_V(6); PG8_BAR; PG8_MMA(1, 1, At, B1); PG8_BAR;
;             PG8_LDB(B0, 1, 0); PG8_SCHED; PG8_LDA(At, 1, 0); PG8_STAGE(PG8_SA(0, 1), a2 + hstep, voffA);
;             PG8_WAIT_L(8); PG8_BAR; PG8_WAIT_L(0); PG8_MMA(0, 0, At, B0); PG8_BAR; PG8_SCHED;
;             PG8_LDB(B1, 1, 1); PG8_STAGE(PG8_SB(1, 0), b3, voffB);
;             PG8_BAR; PG8_WAIT_L(0); PG8_MMA(0, 1, At, B1); PG8_BAR;
;             PG8_LDA(At, 1, 1); PG8_STAGE(PG8_SA(1, 0), a3, voffA);
;             PG8_BAR; PG8_WAIT_L(0); PG8_MMA(1, 0, At, B0); PG8_BAR; PG8_SCHED;
;             PG8_STAGE(PG8_SB(1, 1), b3 + hstep, voffB);
;             PG8_WAIT_V(6); PG8_BAR; PG8_MMA(1, 1, At, B1); PG8_BAR;
	v_mfma_f32_16x16x32_bf16 v[92:95], v[128:131], v[170:173], 0
	v_mfma_f32_16x16x32_bf16 v[88:91], v[154:157], v[170:173], 0
	v_mfma_f32_16x16x32_bf16 v[84:87], v[128:131], v[178:181], 0
	v_mfma_f32_16x16x32_bf16 v[80:83], v[154:157], v[178:181], 0
	v_mfma_f32_16x16x32_bf16 v[76:79], v[128:131], v[186:189], 0
	v_mfma_f32_16x16x32_bf16 v[72:75], v[154:157], v[186:189], 0
	v_mfma_f32_16x16x32_bf16 v[68:71], v[128:131], v[194:197], 0
	v_mfma_f32_16x16x32_bf16 v[64:67], v[154:157], v[194:197], 0
	s_add_i32 s33, 0, 0x18000
	v_add_u32_e32 v144, s33, v160
	v_mfma_f32_16x16x32_bf16 v[92:95], v[132:135], v[174:177], v[92:95]
	v_mfma_f32_16x16x32_bf16 v[88:91], v[166:169], v[174:177], v[88:91]
	v_mfma_f32_16x16x32_bf16 v[84:87], v[132:135], v[182:185], v[84:87]
	v_mfma_f32_16x16x32_bf16 v[80:83], v[166:169], v[182:185], v[80:83]
	v_mfma_f32_16x16x32_bf16 v[76:79], v[132:135], v[190:193], v[76:79]
	v_mfma_f32_16x16x32_bf16 v[72:75], v[166:169], v[190:193], v[72:75]
	v_mfma_f32_16x16x32_bf16 v[68:71], v[132:135], v[198:201], v[68:71]
	v_mfma_f32_16x16x32_bf16 v[64:67], v[166:169], v[198:201], v[64:67]
	v_mfma_f32_16x16x32_bf16 v[28:31], v[202:205], v[170:173], 0
	v_mfma_f32_16x16x32_bf16 v[24:27], v[210:213], v[170:173], 0
	v_mfma_f32_16x16x32_bf16 v[20:23], v[202:205], v[178:181], 0
	v_mfma_f32_16x16x32_bf16 v[16:19], v[210:213], v[178:181], 0
	v_mfma_f32_16x16x32_bf16 v[12:15], v[202:205], v[186:189], 0
	v_mfma_f32_16x16x32_bf16 v[8:11], v[210:213], v[186:189], 0
	v_mfma_f32_16x16x32_bf16 v[4:7], v[202:205], v[194:197], 0
	v_mfma_f32_16x16x32_bf16 v[0:3], v[210:213], v[194:197], 0
	v_mfma_f32_16x16x32_bf16 v[28:31], v[206:209], v[174:177], v[28:31]
	v_mfma_f32_16x16x32_bf16 v[24:27], v[214:217], v[174:177], v[24:27]
	v_mfma_f32_16x16x32_bf16 v[20:23], v[206:209], v[182:185], v[20:23]
	v_mfma_f32_16x16x32_bf16 v[16:19], v[214:217], v[182:185], v[16:19]
	v_mfma_f32_16x16x32_bf16 v[12:15], v[206:209], v[190:193], v[12:15]
	v_mfma_f32_16x16x32_bf16 v[8:11], v[214:217], v[190:193], v[8:11]
	v_mfma_f32_16x16x32_bf16 v[4:7], v[206:209], v[198:201], v[4:7]
	v_mfma_f32_16x16x32_bf16 v[0:3], v[214:217], v[198:201], v[0:3]
	s_barrier
	s_setprio 0
	ds_read_b128 v[128:131], v162 offset:32768
	ds_read_b128 v[132:135], v162 offset:33792
	ds_read_b128 v[154:157], v162 offset:34816
	ds_read_b128 v[166:169], v162 offset:35840
	ds_read_b128 v[170:173], v163 offset:32768
	ds_read_b128 v[174:177], v163 offset:33792
	ds_read_b128 v[178:181], v163 offset:34816
	ds_read_b128 v[182:185], v163 offset:35840
	ds_read_b128 v[186:189], v163 offset:36864
	ds_read_b128 v[190:193], v163 offset:37888
	ds_read_b128 v[194:197], v163 offset:38912
	ds_read_b128 v[198:201], v163 offset:39936
	ds_read_b128 v[202:205], v164 offset:32768
	ds_read_b128 v[206:209], v164 offset:33792
	ds_read_b128 v[210:213], v164 offset:34816
	ds_read_b128 v[214:217], v164 offset:35840
	s_add_u32 s10, s72, 0x80000
	s_addc_u32 s11, s73, 0
	s_mov_b32 m0, s80
	v_lshl_add_u64 v[224:225], s[10:11], 0, v[136:137]
	global_load_lds_dwordx4 v[224:225], off
	v_lshl_add_u64 v[224:225], s[10:11], 0, v[140:141]
	s_mov_b32 m0, s81
	s_nop 0
	global_load_lds_dwordx4 v[224:225], off
	s_waitcnt vmcnt(8)
	s_waitcnt lgkmcnt(0)
	s_setprio 1
	s_barrier
	v_mfma_f32_16x16x32_bf16 v[124:127], v[128:131], v[170:173], v[124:127]
	v_mfma_f32_16x16x32_bf16 v[120:123], v[154:157], v[170:173], v[120:123]
	v_mfma_f32_16x16x32_bf16 v[116:119], v[128:131], v[178:181], v[116:119]
	v_mfma_f32_16x16x32_bf16 v[112:115], v[154:157], v[178:181], v[112:115]
	v_mfma_f32_16x16x32_bf16 v[108:111], v[128:131], v[186:189], v[108:111]
	v_mfma_f32_16x16x32_bf16 v[104:107], v[154:157], v[186:189], v[104:107]
	v_mfma_f32_16x16x32_bf16 v[100:103], v[128:131], v[194:197], v[100:103]
	v_mfma_f32_16x16x32_bf16 v[96:99], v[154:157], v[194:197], v[96:99]
	v_mfma_f32_16x16x32_bf16 v[124:127], v[132:135], v[174:177], v[124:127]
	v_mfma_f32_16x16x32_bf16 v[120:123], v[166:169], v[174:177], v[120:123]
	v_mfma_f32_16x16x32_bf16 v[116:119], v[132:135], v[182:185], v[116:119]
	v_mfma_f32_16x16x32_bf16 v[112:115], v[166:169], v[182:185], v[112:115]
	v_mfma_f32_16x16x32_bf16 v[108:111], v[132:135], v[190:193], v[108:111]
	v_mfma_f32_16x16x32_bf16 v[104:107], v[166:169], v[190:193], v[104:107]
	v_mfma_f32_16x16x32_bf16 v[100:103], v[132:135], v[198:201], v[100:103]
	v_mfma_f32_16x16x32_bf16 v[96:99], v[166:169], v[198:201], v[96:99]
	v_mfma_f32_16x16x32_bf16 v[60:63], v[202:205], v[170:173], v[60:63]
	v_mfma_f32_16x16x32_bf16 v[56:59], v[210:213], v[170:173], v[56:59]
	v_mfma_f32_16x16x32_bf16 v[52:55], v[202:205], v[178:181], v[52:55]
	v_mfma_f32_16x16x32_bf16 v[48:51], v[210:213], v[178:181], v[48:51]
	v_mfma_f32_16x16x32_bf16 v[44:47], v[202:205], v[186:189], v[44:47]
	v_mfma_f32_16x16x32_bf16 v[40:43], v[210:213], v[186:189], v[40:43]
	v_mfma_f32_16x16x32_bf16 v[36:39], v[202:205], v[194:197], v[36:39]
	v_mfma_f32_16x16x32_bf16 v[32:35], v[210:213], v[194:197], v[32:35]
	v_mfma_f32_16x16x32_bf16 v[60:63], v[206:209], v[174:177], v[60:63]
	v_mfma_f32_16x16x32_bf16 v[56:59], v[214:217], v[174:177], v[56:59]
	v_mfma_f32_16x16x32_bf16 v[52:55], v[206:209], v[182:185], v[52:55]
	v_mfma_f32_16x16x32_bf16 v[48:51], v[214:217], v[182:185], v[48:51]
	v_mfma_f32_16x16x32_bf16 v[44:47], v[206:209], v[190:193], v[44:47]
	v_mfma_f32_16x16x32_bf16 v[40:43], v[214:217], v[190:193], v[40:43]
	v_mfma_f32_16x16x32_bf16 v[36:39], v[206:209], v[198:201], v[36:39]
	v_mfma_f32_16x16x32_bf16 v[32:35], v[214:217], v[198:201], v[32:35]
	s_barrier
; #define PG8_STAGE(bufoff, gbase, voff) do { _Pragma("unroll") for (int _i = 0; _i < 2; ++_i) \
;         __builtin_amdgcn_global_load_lds((const unsigned*)((const char*)(gbase) + (voff)[_i]), (PG8_LAS unsigned*)(lds + (bufoff) + ldsw + _i * 8192), 16, 0, 0); } while (0)
; #define PG8_LDA(dst, b, h) do { _Pragma("unroll") for (int m = 0; m < 4; ++m) _Pragma("unroll") for (int k = 0; k < 2; ++k) dst[m][k] = *(const PG8_LAS bf16x8*)(lds + PG8_SA(b, h) + aoff + m * 2048 + k * 1024); } while (0)
; #define PG8_LDB(dst, b, h) do { _Pragma("unroll") for (int n = 0; n < 2; ++n) _Pragma("unroll") for (int k = 0; k < 2; ++k) dst[n][k] = *(const PG8_LAS bf16x8*)(lds + PG8_SB(b, h) + boff + n * 2048 + k * 1024); } while (0)
; #define PG8_WAIT_V(n) asm volatile("s_waitcnt vmcnt(" #n ")" ::: "memory")
; #define PG8_WAIT_L(n) asm volatile("s_waitcnt lgkmcnt(" #n ")" ::: "memory")
; #define PG8_BAR __builtin_amdgcn_s_barrier()
; #define PG8_SCHED __builtin_amdgcn_sched_barrier(0)
; template <class Epi, class Sched>
; __device__ __forceinline__ void gemm_phase(PG8_LAS unsigned char* lds, const Gemm g, const Sched& S, const Epi& E) {
;     ...
;             PG8_LDB(B0, 0, 0); PG8_SCHED; PG8_LDA(At, 0, 0); PG8_STAGE(PG8_SA(1, 1), a1 + hstep, voffA);
;             PG8_WAIT_L(8); PG8_BAR; PG8_WAIT_L(0); PG8_MMA(0, 0, At, B0); PG8_BAR; PG8_SCHED;
;             PG8_LDB(B1, 0, 1); PG8_STAGE(PG8_SB(0, 0), b2, voffB);
;             PG8_BAR; PG8_WAIT_L(0); PG8_MMA(0, 1, At, B1); PG8_BAR;
;             PG8_LDA(At, 0, 1); PG8_STAGE(PG8_SA(0, 0), a2, voffA);
;             PG8_BAR; PG8_WAIT_L(0); PG8_MMA(1, 0, At, B0); PG8_BAR; PG8_SCHED;
;             PG8_STAGE(PG8_SB(0, 1), b2 + hstep, voffB);
;             PG8_WAIT_V(6); PG8_BAR; PG8_MMA(1, 1, At, B1); PG8_BAR;
;             PG8_LDB(B0, 1, 0); PG8_SCHED; PG8_LDA(At, 1, 0); PG8_STAGE(PG8_SA(0, 1), a2 + hstep, voffA);
;             PG8_WAIT_L(8); PG8_BAR; PG8_WAIT_L(0); PG8_MMA(0, 0, At, B0); PG8_BAR; PG8_SCHED;
;             PG8_LDB(B1, 1, 1); PG8_STAGE(PG8_SB(1, 0), b3, voffB);
;             PG8_BAR; PG8_WAIT_L(0); PG8_MMA(0, 1, At, B1); PG8_BAR;
;             PG8_LDA(At, 1, 1); PG8_STAGE(PG8_SA(1, 0), a3, voffA);
;             PG8_BAR; PG8_WAIT_L(0); PG8_MMA(1, 0, At, B0); PG8_BAR; PG8_SCHED;
;             PG8_STAGE(PG8_SB(1, 1), b3 + hstep, voffB);
;             PG8_WAIT_V(6); PG8_BAR; PG8_MMA(1, 1, At, B1); PG8_BAR;
;         }
	s_setprio 0
	ds_read_b128 v[170:173], v163 offset:49152
	ds_read_b128 v[174:177], v163 offset:50176
	ds_read_b128 v[178:181], v163 offset:51200
	ds_read_b128 v[182:185], v163 offset:52224
	ds_read_b128 v[186:189], v163 offset:53248
	ds_read_b128 v[190:193], v163 offset:54272
	ds_read_b128 v[194:197], v163 offset:55296
	ds_read_b128 v[198:201], v163 offset:56320
	s_add_i32 s72, 0, 0x1c000
	s_add_i32 s10, s33, s78
	v_add_u32_e32 v144, s72, v160
	v_lshl_add_u64 v[158:159], v[158:159], 0, s[26:27]
	s_mov_b32 m0, s10
	s_nop 0
	global_load_lds_dwordx4 v[158:159], off
	v_lshl_add_u64 v[158:159], v[218:219], 0, s[26:27]
	s_add_i32 m0, s10, 0x2000
	s_nop 0
	global_load_lds_dwordx4 v[158:159], off
	s_mov_b32 m0, s84
	v_lshl_add_u64 v[158:159], v[220:221], 0, s[26:27]
	global_load_lds_dwordx4 v[158:159], off
	v_lshl_add_u64 v[158:159], v[222:223], 0, s[26:27]
	s_mov_b32 m0, s85
	s_nop 0
	global_load_lds_dwordx4 v[158:159], off
	s_add_u32 s10, s70, 0x80080
	s_addc_u32 s11, s71, 0
	s_add_i32 s33, s72, s78
	v_lshl_add_u64 v[224:225], s[10:11], 0, v[138:139]
	s_mov_b32 m0, s33
	s_nop 0
	global_load_lds_dwordx4 v[224:225], off
	v_lshl_add_u64 v[224:225], s[10:11], 0, v[142:143]
	s_add_i32 m0, s33, 0x2000
	s_nop 0
	global_load_lds_dwordx4 v[224:225], off
	s_waitcnt vmcnt(8)
	s_waitcnt lgkmcnt(0)
	s_setprio 1
	s_barrier
	v_mfma_f32_16x16x32_bf16 v[92:95], v[128:131], v[170:173], v[92:95]
	v_mfma_f32_16x16x32_bf16 v[88:91], v[154:157], v[170:173], v[88:91]
	v_mfma_f32_16x16x32_bf16 v[84:87], v[128:131], v[178:181], v[84:87]
	v_mfma_f32_16x16x32_bf16 v[80:83], v[154:157], v[178:181], v[80:83]
	v_mfma_f32_16x16x32_bf16 v[76:79], v[128:131], v[186:189], v[76:79]
	v_mfma_f32_16x16x32_bf16 v[72:75], v[154:157], v[186:189], v[72:75]
	v_mfma_f32_16x16x32_bf16 v[68:71], v[128:131], v[194:197], v[68:71]
	v_mfma_f32_16x16x32_bf16 v[64:67], v[154:157], v[194:197], v[64:67]
	s_add_i32 vcc_hi, vcc_hi, 2
	s_add_u32 s68, s68, 0x100
	s_addc_u32 s69, s69, 0
	s_add_u32 s97, s97, 0x100
	s_addc_u32 vcc_lo, vcc_lo, 0
	s_cmp_gt_u32 vcc_hi, 29
	v_mfma_f32_16x16x32_bf16 v[92:95], v[132:135], v[174:177], v[92:95]
	v_mfma_f32_16x16x32_bf16 v[88:91], v[166:169], v[174:177], v[88:91]
	v_mfma_f32_16x16x32_bf16 v[84:87], v[132:135], v[182:185], v[84:87]
	v_mfma_f32_16x16x32_bf16 v[80:83], v[166:169], v[182:185], v[80:83]
	v_mfma_f32_16x16x32_bf16 v[76:79], v[132:135], v[190:193], v[76:79]
	v_mfma_f32_16x16x32_bf16 v[72:75], v[166:169], v[190:193], v[72:75]
	v_mfma_f32_16x16x32_bf16 v[68:71], v[132:135], v[198:201], v[68:71]
	v_mfma_f32_16x16x32_bf16 v[64:67], v[166:169], v[198:201], v[64:67]
	v_mfma_f32_16x16x32_bf16 v[28:31], v[202:205], v[170:173], v[28:31]
	v_mfma_f32_16x16x32_bf16 v[24:27], v[210:213], v[170:173], v[24:27]
	v_mfma_f32_16x16x32_bf16 v[20:23], v[202:205], v[178:181], v[20:23]
	v_mfma_f32_16x16x32_bf16 v[16:19], v[210:213], v[178:181], v[16:19]
	v_mfma_f32_16x16x32_bf16 v[12:15], v[202:205], v[186:189], v[12:15]
	v_mfma_f32_16x16x32_bf16 v[8:11], v[210:213], v[186:189], v[8:11]
	v_mfma_f32_16x16x32_bf16 v[4:7], v[202:205], v[194:197], v[4:7]
	v_mfma_f32_16x16x32_bf16 v[0:3], v[210:213], v[194:197], v[0:3]
	v_mfma_f32_16x16x32_bf16 v[28:31], v[206:209], v[174:177], v[28:31]
	v_mfma_f32_16x16x32_bf16 v[24:27], v[214:217], v[174:177], v[24:27]
	v_mfma_f32_16x16x32_bf16 v[20:23], v[206:209], v[182:185], v[20:23]
	v_mfma_f32_16x16x32_bf16 v[16:19], v[214:217], v[182:185], v[16:19]
	v_mfma_f32_16x16x32_bf16 v[12:15], v[206:209], v[190:193], v[12:15]
	v_mfma_f32_16x16x32_bf16 v[8:11], v[214:217], v[190:193], v[8:11]
	v_mfma_f32_16x16x32_bf16 v[4:7], v[206:209], v[198:201], v[4:7]
	v_mfma_f32_16x16x32_bf16 v[0:3], v[214:217], v[198:201], v[0:3]
	s_barrier

; #define PG8_STAGE(bufoff, gbase, voff) do { _Pragma("unroll") for (int _i = 0; _i < 2; ++_i) \
;         __builtin_amdgcn_global_load_lds((const unsigned*)((const char*)(gbase) + (voff)[_i]), (PG8_LAS unsigned*)(lds + (bufoff) + ldsw + _i * 8192), 16, 0, 0); } while (0)
; #define PG8_WAIT_V(n) asm volatile("s_waitcnt vmcnt(" #n ")" ::: "memory")
; template <class Epi, class Sched>
; __device__ __forceinline__ void gemm_phase(PG8_LAS unsigned char* lds, const Gemm g, const Sched& S, const Epi& E) {
;     ...
;     for (;;) {
;         const bool has_next = S.next(ui + 1, nxt);
;         const char* nA = has_next ? (const char*)g.A + (size_t)nxt.pm * tstep : cA; const char* nB = has_next ? (const char*)g.Bt + (size_t)nxt.pn * tstep : cB;
;         for (int t = 0; t < nt; t += 2) {
;             const bool last = (t == nt - 2);
;             const char* a1 = cA + (size_t)(t + 1) * kstep;
;             const char* a2 = last ? nA : cA + (size_t)(t + 2) * kstep; const char* b2 = last ? nB : cB + (size_t)(t + 2) * kstep;
;             const char* a3 = a2 + kstep; const char* b3 = b2 + kstep;
;             if (last && has_next) S.a_ready(nxt);
;             PG8_LDB(B0, 0, 0); PG8_SCHED; PG8_LDA(At, 0, 0); PG8_STAGE(PG8_SA(1, 1), a1 + hstep, voffA);
;             PG8_WAIT_L(8); PG8_BAR; PG8_WAIT_L(0); PG8_MMA(0, 0, At, B0); PG8_BAR; PG8_SCHED;
;             PG8_LDB(B1, 0, 1); PG8_STAGE(PG8_SB(0, 0), b2, voffB);
;             PG8_BAR; PG8_WAIT_L(0); PG8_MMA(0, 1, At, B1); PG8_BAR;
;             PG8_LDA(At, 0, 1); PG8_STAGE(PG8_SA(0, 0), a2, voffA);
;             PG8_BAR; PG8_WAIT_L(0); PG8_MMA(1, 0, At, B0); PG8_BAR; PG8_SCHED;
;             PG8_STAGE(PG8_SB(0, 1), b2 + hstep, voffB);
;             PG8_WAIT_V(6); PG8_BAR; PG8_MMA(1, 1, At, B1); PG8_BAR;
;             PG8_LDB(B0, 1, 0); PG8_SCHED; PG8_LDA(At, 1, 0); PG8_STAGE(PG8_SA(0, 1), a2 + hstep, voffA);
;             PG8_WAIT_L(8); PG8_BAR; PG8_WAIT_L(0); PG8_MMA(0, 0, At, B0); PG8_BAR; PG8_SCHED;
;             PG8_LDB(B1, 1, 1); PG8_STAGE(PG8_SB(1, 0), b3, voffB);
;             PG8_BAR; PG8_WAIT_L(0); PG8_MMA(0, 1, At, B1); PG8_BAR;
;             PG8_LDA(At, 1, 1); PG8_STAGE(PG8_SA(1, 0), a3, voffA);
;             PG8_BAR; PG8_WAIT_L(0); PG8_MMA(1, 0, At, B0); PG8_BAR; PG8_SCHED;
;             PG8_STAGE(PG8_SB(1, 1), b3 + hstep, voffB);
;             PG8_WAIT_V(6); PG8_BAR; PG8_MMA(1, 1, At, B1); PG8_BAR;
.LBB0_665:
	s_ashr_i32 s19, s18, 31
	s_lshl_b64 s[10:11], s[18:19], 20
	v_cmp_lt_i64_e32 vcc, s[20:21], v[156:157]
	s_add_u32 s20, s41, s10
	s_addc_u32 s21, s42, s11
	s_and_b64 s[10:11], vcc, exec
	s_cselect_b32 s19, s21, s31
	s_cselect_b32 s70, s20, s30
	s_ashr_i32 s17, s16, 31
	s_lshl_b64 s[10:11], s[16:17], 20
	s_add_u32 s26, s43, s10
	s_addc_u32 s27, s44, s11
	s_and_b64 s[10:11], vcc, exec
	s_cselect_b32 s17, s27, s35
	s_cselect_b32 s71, s26, s34
	s_add_u32 s30, s30, 0x80080
	s_addc_u32 s31, s31, 0
	s_add_u32 s72, s34, 0x100
	s_addc_u32 s73, s35, 0
	s_mov_b32 s74, -2
	s_setprio 0
	ds_read_b128 v[128:131], v169
	ds_read_b128 v[132:135], v169 offset:1024
	ds_read_b128 v[136:139], v169 offset:2048
	ds_read_b128 v[140:143], v169 offset:3072
	ds_read_b128 v[160:163], v170
	ds_read_b128 v[172:175], v170 offset:1024
	ds_read_b128 v[176:179], v170 offset:2048
	ds_read_b128 v[180:183], v170 offset:3072
	ds_read_b128 v[184:187], v170 offset:4096
	ds_read_b128 v[188:191], v170 offset:5120
	ds_read_b128 v[192:195], v170 offset:6144
	ds_read_b128 v[196:199], v170 offset:7168
	ds_read_b128 v[200:203], v171
	ds_read_b128 v[204:207], v171 offset:1024
	ds_read_b128 v[208:211], v171 offset:2048
	ds_read_b128 v[212:215], v171 offset:3072
	s_add_u32 s10, s30, 0xfff80080
	s_addc_u32 s11, s31, -1
	s_cmp_eq_u32 s74, 28
	s_cselect_b32 s39, s19, s11
	s_cselect_b32 s38, s70, s10
	s_cselect_b32 s35, s17, s73
	s_cselect_b32 s34, s71, s72
	v_lshl_add_u64 v[164:165], s[30:31], 0, v[152:153]
	s_add_i32 m0, s29, 0xc000
	s_nop 0
	global_load_lds_dwordx4 v[164:165], off
	v_lshl_add_u64 v[164:165], s[30:31], 0, v[154:155]
	s_add_i32 m0, s29, 0xe000
	s_nop 0
	global_load_lds_dwordx4 v[164:165], off
	s_waitcnt vmcnt(8)
	s_waitcnt lgkmcnt(0)
	s_setprio 1
	s_barrier
	v_mfma_f32_16x16x32_bf16 v[120:123], v[128:131], v[160:163], 0
	v_mfma_f32_16x16x32_bf16 v[124:127], v[136:139], v[160:163], 0
	v_mfma_f32_16x16x32_bf16 v[112:115], v[128:131], v[176:179], 0
	v_mfma_f32_16x16x32_bf16 v[116:119], v[136:139], v[176:179], 0
	v_mfma_f32_16x16x32_bf16 v[96:99], v[128:131], v[184:187], 0
	v_mfma_f32_16x16x32_bf16 v[88:91], v[136:139], v[184:187], 0
	v_mfma_f32_16x16x32_bf16 v[80:83], v[128:131], v[192:195], 0
	v_mfma_f32_16x16x32_bf16 v[72:75], v[136:139], v[192:195], 0
	v_mfma_f32_16x16x32_bf16 v[120:123], v[132:135], v[172:175], v[120:123]
	v_mfma_f32_16x16x32_bf16 v[124:127], v[140:143], v[172:175], v[124:127]
	v_mfma_f32_16x16x32_bf16 v[112:115], v[132:135], v[180:183], v[112:115]
	v_mfma_f32_16x16x32_bf16 v[116:119], v[140:143], v[180:183], v[116:119]
	v_mfma_f32_16x16x32_bf16 v[96:99], v[132:135], v[188:191], v[96:99]
	v_mfma_f32_16x16x32_bf16 v[88:91], v[140:143], v[188:191], v[88:91]
	v_mfma_f32_16x16x32_bf16 v[80:83], v[132:135], v[196:199], v[80:83]
	v_mfma_f32_16x16x32_bf16 v[72:75], v[140:143], v[196:199], v[72:75]
	v_mfma_f32_16x16x32_bf16 v[108:111], v[200:203], v[160:163], 0
	v_mfma_f32_16x16x32_bf16 v[104:107], v[208:211], v[160:163], 0
	v_mfma_f32_16x16x32_bf16 v[100:103], v[200:203], v[176:179], 0
	v_mfma_f32_16x16x32_bf16 v[92:95], v[208:211], v[176:179], 0
	v_mfma_f32_16x16x32_bf16 v[84:87], v[200:203], v[184:187], 0
	v_mfma_f32_16x16x32_bf16 v[76:79], v[208:211], v[184:187], 0
	v_mfma_f32_16x16x32_bf16 v[68:71], v[200:203], v[192:195], 0
	v_mfma_f32_16x16x32_bf16 v[64:67], v[208:211], v[192:195], 0
	v_mfma_f32_16x16x32_bf16 v[108:111], v[204:207], v[172:175], v[108:111]
	v_mfma_f32_16x16x32_bf16 v[104:107], v[212:215], v[172:175], v[104:107]
	v_mfma_f32_16x16x32_bf16 v[100:103], v[204:207], v[180:183], v[100:103]
	v_mfma_f32_16x16x32_bf16 v[92:95], v[212:215], v[180:183], v[92:95]
	v_mfma_f32_16x16x32_bf16 v[84:87], v[204:207], v[188:191], v[84:87]
	v_mfma_f32_16x16x32_bf16 v[76:79], v[212:215], v[188:191], v[76:79]
	v_mfma_f32_16x16x32_bf16 v[68:71], v[204:207], v[196:199], v[68:71]
	v_mfma_f32_16x16x32_bf16 v[64:67], v[212:215], v[196:199], v[64:67]
	s_barrier
	s_setprio 0
	ds_read_b128 v[160:163], v170 offset:16384
	ds_read_b128 v[172:175], v170 offset:17408
	ds_read_b128 v[176:179], v170 offset:18432
	ds_read_b128 v[180:183], v170 offset:19456
	ds_read_b128 v[184:187], v170 offset:20480
	ds_read_b128 v[188:191], v170 offset:21504
	ds_read_b128 v[192:195], v170 offset:22528
	ds_read_b128 v[196:199], v170 offset:23552
	s_add_i32 s10, s66, s45
	v_lshl_add_u64 v[164:165], s[34:35], 0, v[146:147]
	s_mov_b32 m0, s10
	s_nop 0
	global_load_lds_dwordx4 v[164:165], off
	v_lshl_add_u64 v[216:217], s[34:35], 0, v[150:151]
	s_add_i32 m0, s10, 0x2000
	s_nop 0
	global_load_lds_dwordx4 v[216:217], off
	s_mov_b32 m0, s29
	v_lshl_add_u64 v[218:219], s[38:39], 0, v[144:145]
	global_load_lds_dwordx4 v[218:219], off
	v_lshl_add_u64 v[220:221], s[38:39], 0, v[148:149]
	s_mov_b32 m0, s46
	s_nop 0
	global_load_lds_dwordx4 v[220:221], off
	s_add_u32 s10, s34, 0x80000
	s_addc_u32 s11, s35, 0
	s_add_i32 s33, s67, s45
	v_lshl_add_u64 v[246:247], s[10:11], 0, v[146:147]
	s_mov_b32 m0, s33
	s_nop 0
	global_load_lds_dwordx4 v[246:247], off
	v_lshl_add_u64 v[246:247], s[10:11], 0, v[150:151]
	s_add_i32 m0, s33, 0x2000
	s_nop 0
	global_load_lds_dwordx4 v[246:247], off
	s_waitcnt vmcnt(8)
	s_waitcnt lgkmcnt(0)
	s_setprio 1
	s_barrier
; #define PG8_STAGE(bufoff, gbase, voff) do { _Pragma("unroll") for (int _i = 0; _i < 2; ++_i) \
;         __builtin_amdgcn_global_load_lds((const unsigned*)((const char*)(gbase) + (voff)[_i]), (PG8_LAS unsigned*)(lds + (bufoff) + ldsw + _i * 8192), 16, 0, 0); } while (0)
; #define PG8_LDA(dst, b, h) do { _Pragma("unroll") for (int m = 0; m < 4; ++m) _Pragma("unroll") for (int k = 0; k < 2; ++k) dst[m][k] = *(const PG8_LAS bf16x8*)(lds + PG8_SA(b, h) + aoff + m * 2048 + k * 1024); } while (0)
; #define PG8_LDB(dst, b, h) do { _Pragma("unroll") for (int n = 0; n < 2; ++n) _Pragma("unroll") for (int k = 0; k < 2; ++k) dst[n][k] = *(const PG8_LAS bf16x8*)(lds + PG8_SB(b, h) + boff + n * 2048 + k * 1024); } while (0)
; #define PG8_WAIT_V(n) asm volatile("s_waitcnt vmcnt(" #n ")" ::: "memory")
; #define PG8_WAIT_L(n) asm volatile("s_waitcnt lgkmcnt(" #n ")" ::: "memory")
; #define PG8_BAR __builtin_amdgcn_s_barrier()
; #define PG8_SCHED __builtin_amdgcn_sched_barrier(0)
; template <class Epi, class Sched>
; __device__ __forceinline__ void gemm_phase(PG8_LAS unsigned char* lds, const Gemm g, const Sched& S, const Epi& E) {
;     ...
;             PG8_LDB(B0, 0, 0); PG8_SCHED; PG8_LDA(At, 0, 0); PG8_STAGE(PG8_SA(1, 1), a1 + hstep, voffA);
;             PG8_WAIT_L(8); PG8_BAR; PG8_WAIT_L(0); PG8_MMA(0, 0, At, B0); PG8_BAR; PG8_SCHED;
;             PG8_LDB(B1, 0, 1); PG8_STAGE(PG8_SB(0, 0), b2, voffB);
;             PG8_BAR; PG8_WAIT_L(0); PG8_MMA(0, 1, At, B1); PG8_BAR;
;             PG8_LDA(At, 0, 1); PG8_STAGE(PG8_SA(0, 0), a2, voffA);
;             PG8_BAR; PG8_WAIT_L(0); PG8_MMA(1, 0, At, B0); PG8_BAR; PG8_SCHED;
;             PG8_STAGE(PG8_SB(0, 1), b2 + hstep, voffB);
;             PG8_WAIT_V(6); PG8_BAR; PG8_MMA(1, 1, At, B1); PG8_BAR;
;             PG8_LDB(B0, 1, 0); PG8_SCHED; PG8_LDA(At, 1, 0); PG8_STAGE(PG8_SA(0, 1), a2 + hstep, voffA);
;             PG8_WAIT_L(8); PG8_BAR; PG8_WAIT_L(0); PG8_MMA(0, 0, At, B0); PG8_BAR; PG8_SCHED;
;             PG8_LDB(B1, 1, 1); PG8_STAGE(PG8_SB(1, 0), b3, voffB);
;             PG8_BAR; PG8_WAIT_L(0); PG8_MMA(0, 1, At, B1); PG8_BAR;
;             PG8_LDA(At, 1, 1); PG8_STAGE(PG8_SA(1, 0), a3, voffA);
;             PG8_BAR; PG8_WAIT_L(0); PG8_MMA(1, 0, At, B0); PG8_BAR; PG8_SCHED;
;             PG8_STAGE(PG8_SB(1, 1), b3 + hstep, voffB);
;             PG8_WAIT_V(6); PG8_BAR; PG8_MMA(1, 1, At, B1); PG8_BAR;
	v_mfma_f32_16x16x32_bf16 v[60:63], v[128:131], v[160:163], 0
	v_mfma_f32_16x16x32_bf16 v[56:59], v[136:139], v[160:163], 0
	v_mfma_f32_16x16x32_bf16 v[48:51], v[128:131], v[176:179], 0
	v_mfma_f32_16x16x32_bf16 v[40:43], v[136:139], v[176:179], 0
	v_mfma_f32_16x16x32_bf16 v[32:35], v[128:131], v[184:187], 0
	v_mfma_f32_16x16x32_bf16 v[24:27], v[136:139], v[184:187], 0
	v_mfma_f32_16x16x32_bf16 v[16:19], v[128:131], v[192:195], 0
	v_mfma_f32_16x16x32_bf16 v[8:11], v[136:139], v[192:195], 0
	s_add_i32 s33, 0, 0x18000
	v_mfma_f32_16x16x32_bf16 v[60:63], v[132:135], v[172:175], v[60:63]
	v_mfma_f32_16x16x32_bf16 v[56:59], v[140:143], v[172:175], v[56:59]
	v_mfma_f32_16x16x32_bf16 v[48:51], v[132:135], v[180:183], v[48:51]
	v_mfma_f32_16x16x32_bf16 v[40:43], v[140:143], v[180:183], v[40:43]
	v_mfma_f32_16x16x32_bf16 v[32:35], v[132:135], v[188:191], v[32:35]
	v_mfma_f32_16x16x32_bf16 v[24:27], v[140:143], v[188:191], v[24:27]
	v_mfma_f32_16x16x32_bf16 v[16:19], v[132:135], v[196:199], v[16:19]
	v_mfma_f32_16x16x32_bf16 v[8:11], v[140:143], v[196:199], v[8:11]
	v_mfma_f32_16x16x32_bf16 v[52:55], v[200:203], v[160:163], 0
	v_mfma_f32_16x16x32_bf16 v[44:47], v[208:211], v[160:163], 0
	v_mfma_f32_16x16x32_bf16 v[36:39], v[200:203], v[176:179], 0
	v_mfma_f32_16x16x32_bf16 v[28:31], v[208:211], v[176:179], 0
	v_mfma_f32_16x16x32_bf16 v[20:23], v[200:203], v[184:187], 0
	v_mfma_f32_16x16x32_bf16 v[12:15], v[208:211], v[184:187], 0
	v_mfma_f32_16x16x32_bf16 v[4:7], v[200:203], v[192:195], 0
	v_mfma_f32_16x16x32_bf16 v[0:3], v[208:211], v[192:195], 0
	v_mfma_f32_16x16x32_bf16 v[52:55], v[204:207], v[172:175], v[52:55]
	v_mfma_f32_16x16x32_bf16 v[44:47], v[212:215], v[172:175], v[44:47]
	v_mfma_f32_16x16x32_bf16 v[36:39], v[204:207], v[180:183], v[36:39]
	v_mfma_f32_16x16x32_bf16 v[28:31], v[212:215], v[180:183], v[28:31]
	v_mfma_f32_16x16x32_bf16 v[20:23], v[204:207], v[188:191], v[20:23]
	v_mfma_f32_16x16x32_bf16 v[12:15], v[212:215], v[188:191], v[12:15]
	v_mfma_f32_16x16x32_bf16 v[4:7], v[204:207], v[196:199], v[4:7]
	v_mfma_f32_16x16x32_bf16 v[0:3], v[212:215], v[196:199], v[0:3]
	s_barrier
	s_setprio 0
	ds_read_b128 v[128:131], v169 offset:32768
	ds_read_b128 v[132:135], v169 offset:33792
	ds_read_b128 v[136:139], v169 offset:34816
	ds_read_b128 v[140:143], v169 offset:35840
	ds_read_b128 v[160:163], v170 offset:32768
	ds_read_b128 v[172:175], v170 offset:33792
	ds_read_b128 v[176:179], v170 offset:34816
	ds_read_b128 v[180:183], v170 offset:35840
	ds_read_b128 v[184:187], v170 offset:36864
	ds_read_b128 v[188:191], v170 offset:37888
	ds_read_b128 v[192:195], v170 offset:38912
	ds_read_b128 v[196:199], v170 offset:39936
	ds_read_b128 v[200:203], v171 offset:32768
	ds_read_b128 v[204:207], v171 offset:33792
	ds_read_b128 v[208:211], v171 offset:34816
	ds_read_b128 v[212:215], v171 offset:35840
	s_add_u32 s10, s38, 0x80000
	s_addc_u32 s11, s39, 0
	s_mov_b32 m0, s47
	v_lshl_add_u64 v[246:247], s[10:11], 0, v[144:145]
	global_load_lds_dwordx4 v[246:247], off
	v_lshl_add_u64 v[246:247], s[10:11], 0, v[148:149]
	s_mov_b32 m0, s48
	s_nop 0
	global_load_lds_dwordx4 v[246:247], off
	s_waitcnt vmcnt(8)
	s_waitcnt lgkmcnt(0)
	s_setprio 1
	s_barrier
	v_mfma_f32_16x16x32_bf16 v[120:123], v[128:131], v[160:163], v[120:123]
	v_mfma_f32_16x16x32_bf16 v[124:127], v[136:139], v[160:163], v[124:127]
	v_mfma_f32_16x16x32_bf16 v[112:115], v[128:131], v[176:179], v[112:115]
	v_mfma_f32_16x16x32_bf16 v[116:119], v[136:139], v[176:179], v[116:119]
	v_mfma_f32_16x16x32_bf16 v[96:99], v[128:131], v[184:187], v[96:99]
	v_mfma_f32_16x16x32_bf16 v[88:91], v[136:139], v[184:187], v[88:91]
	v_mfma_f32_16x16x32_bf16 v[80:83], v[128:131], v[192:195], v[80:83]
	v_mfma_f32_16x16x32_bf16 v[72:75], v[136:139], v[192:195], v[72:75]
	v_mfma_f32_16x16x32_bf16 v[120:123], v[132:135], v[172:175], v[120:123]
	v_mfma_f32_16x16x32_bf16 v[124:127], v[140:143], v[172:175], v[124:127]
	v_mfma_f32_16x16x32_bf16 v[112:115], v[132:135], v[180:183], v[112:115]
	v_mfma_f32_16x16x32_bf16 v[116:119], v[140:143], v[180:183], v[116:119]
	v_mfma_f32_16x16x32_bf16 v[96:99], v[132:135], v[188:191], v[96:99]
	v_mfma_f32_16x16x32_bf16 v[88:91], v[140:143], v[188:191], v[88:91]
	v_mfma_f32_16x16x32_bf16 v[80:83], v[132:135], v[196:199], v[80:83]
	v_mfma_f32_16x16x32_bf16 v[72:75], v[140:143], v[196:199], v[72:75]
	v_mfma_f32_16x16x32_bf16 v[108:111], v[200:203], v[160:163], v[108:111]
	v_mfma_f32_16x16x32_bf16 v[104:107], v[208:211], v[160:163], v[104:107]
	v_mfma_f32_16x16x32_bf16 v[100:103], v[200:203], v[176:179], v[100:103]
	v_mfma_f32_16x16x32_bf16 v[92:95], v[208:211], v[176:179], v[92:95]
	v_mfma_f32_16x16x32_bf16 v[84:87], v[200:203], v[184:187], v[84:87]
	v_mfma_f32_16x16x32_bf16 v[76:79], v[208:211], v[184:187], v[76:79]
	v_mfma_f32_16x16x32_bf16 v[68:71], v[200:203], v[192:195], v[68:71]
	v_mfma_f32_16x16x32_bf16 v[64:67], v[208:211], v[192:195], v[64:67]
	v_mfma_f32_16x16x32_bf16 v[108:111], v[204:207], v[172:175], v[108:111]
	v_mfma_f32_16x16x32_bf16 v[104:107], v[212:215], v[172:175], v[104:107]
	v_mfma_f32_16x16x32_bf16 v[100:103], v[204:207], v[180:183], v[100:103]
	v_mfma_f32_16x16x32_bf16 v[92:95], v[212:215], v[180:183], v[92:95]
	v_mfma_f32_16x16x32_bf16 v[84:87], v[204:207], v[188:191], v[84:87]
	v_mfma_f32_16x16x32_bf16 v[76:79], v[212:215], v[188:191], v[76:79]
	v_mfma_f32_16x16x32_bf16 v[68:71], v[204:207], v[196:199], v[68:71]
	v_mfma_f32_16x16x32_bf16 v[64:67], v[212:215], v[196:199], v[64:67]
	s_barrier
; #define PG8_STAGE(bufoff, gbase, voff) do { _Pragma("unroll") for (int _i = 0; _i < 2; ++_i) \
;         __builtin_amdgcn_global_load_lds((const unsigned*)((const char*)(gbase) + (voff)[_i]), (PG8_LAS unsigned*)(lds + (bufoff) + ldsw + _i * 8192), 16, 0, 0); } while (0)
; #define PG8_LDA(dst, b, h) do { _Pragma("unroll") for (int m = 0; m < 4; ++m) _Pragma("unroll") for (int k = 0; k < 2; ++k) dst[m][k] = *(const PG8_LAS bf16x8*)(lds + PG8_SA(b, h) + aoff + m * 2048 + k * 1024); } while (0)
; #define PG8_LDB(dst, b, h) do { _Pragma("unroll") for (int n = 0; n < 2; ++n) _Pragma("unroll") for (int k = 0; k < 2; ++k) dst[n][k] = *(const PG8_LAS bf16x8*)(lds + PG8_SB(b, h) + boff + n * 2048 + k * 1024); } while (0)
; #define PG8_WAIT_V(n) asm volatile("s_waitcnt vmcnt(" #n ")" ::: "memory")
; #define PG8_WAIT_L(n) asm volatile("s_waitcnt lgkmcnt(" #n ")" ::: "memory")
; #define PG8_BAR __builtin_amdgcn_s_barrier()
; #define PG8_SCHED __builtin_amdgcn_sched_barrier(0)
; template <class Epi, class Sched>
; __device__ __forceinline__ void gemm_phase(PG8_LAS unsigned char* lds, const Gemm g, const Sched& S, const Epi& E) {
;     ...
;             PG8_LDB(B0, 0, 0); PG8_SCHED; PG8_LDA(At, 0, 0); PG8_STAGE(PG8_SA(1, 1), a1 + hstep, voffA);
;             PG8_WAIT_L(8); PG8_BAR; PG8_WAIT_L(0); PG8_MMA(0, 0, At, B0); PG8_BAR; PG8_SCHED;
;             PG8_LDB(B1, 0, 1); PG8_STAGE(PG8_SB(0, 0), b2, voffB);
;             PG8_BAR; PG8_WAIT_L(0); PG8_MMA(0, 1, At, B1); PG8_BAR;
;             PG8_LDA(At, 0, 1); PG8_STAGE(PG8_SA(0, 0), a2, voffA);
;             PG8_BAR; PG8_WAIT_L(0); PG8_MMA(1, 0, At, B0); PG8_BAR; PG8_SCHED;
;             PG8_STAGE(PG8_SB(0, 1), b2 + hstep, voffB);
;             PG8_WAIT_V(6); PG8_BAR; PG8_MMA(1, 1, At, B1); PG8_BAR;
;             PG8_LDB(B0, 1, 0); PG8_SCHED; PG8_LDA(At, 1, 0); PG8_STAGE(PG8_SA(0, 1), a2 + hstep, voffA);
;             PG8_WAIT_L(8); PG8_BAR; PG8_WAIT_L(0); PG8_MMA(0, 0, At, B0); PG8_BAR; PG8_SCHED;
;             PG8_LDB(B1, 1, 1); PG8_STAGE(PG8_SB(1, 0), b3, voffB);
;             PG8_BAR; PG8_WAIT_L(0); PG8_MMA(0, 1, At, B1); PG8_BAR;
;             PG8_LDA(At, 1, 1); PG8_STAGE(PG8_SA(1, 0), a3, voffA);
;             PG8_BAR; PG8_WAIT_L(0); PG8_MMA(1, 0, At, B0); PG8_BAR; PG8_SCHED;
;             PG8_STAGE(PG8_SB(1, 1), b3 + hstep, voffB);
;             PG8_WAIT_V(6); PG8_BAR; PG8_MMA(1, 1, At, B1); PG8_BAR;
;         }
	s_setprio 0
	ds_read_b128 v[160:163], v170 offset:49152
	ds_read_b128 v[172:175], v170 offset:50176
	ds_read_b128 v[176:179], v170 offset:51200
	ds_read_b128 v[180:183], v170 offset:52224
	ds_read_b128 v[184:187], v170 offset:53248
	ds_read_b128 v[188:191], v170 offset:54272
	ds_read_b128 v[192:195], v170 offset:55296
	ds_read_b128 v[196:199], v170 offset:56320
	s_add_i32 s38, 0, 0x1c000
	s_add_i32 s10, s33, s45
	v_lshl_add_u64 v[164:165], v[164:165], 0, s[4:5]
	s_mov_b32 m0, s10
	s_nop 0
	global_load_lds_dwordx4 v[164:165], off
	v_lshl_add_u64 v[164:165], v[216:217], 0, s[4:5]
	s_add_i32 m0, s10, 0x2000
	s_nop 0
	global_load_lds_dwordx4 v[164:165], off
	s_mov_b32 m0, s50
	v_lshl_add_u64 v[164:165], v[218:219], 0, s[4:5]
	global_load_lds_dwordx4 v[164:165], off
	v_lshl_add_u64 v[164:165], v[220:221], 0, s[4:5]
	s_mov_b32 m0, s51
	s_nop 0
	global_load_lds_dwordx4 v[164:165], off
	s_add_u32 s10, s34, 0x80080
	s_addc_u32 s11, s35, 0
	s_add_i32 s33, s38, s45
	v_lshl_add_u64 v[246:247], s[10:11], 0, v[146:147]
	s_mov_b32 m0, s33
	s_nop 0
	global_load_lds_dwordx4 v[246:247], off
	v_lshl_add_u64 v[246:247], s[10:11], 0, v[150:151]
	s_add_i32 m0, s33, 0x2000
	s_nop 0
	global_load_lds_dwordx4 v[246:247], off
	s_waitcnt vmcnt(8)
	s_waitcnt lgkmcnt(0)
	s_setprio 1
	s_barrier
	v_mfma_f32_16x16x32_bf16 v[60:63], v[128:131], v[160:163], v[60:63]
	v_mfma_f32_16x16x32_bf16 v[56:59], v[136:139], v[160:163], v[56:59]
	v_mfma_f32_16x16x32_bf16 v[48:51], v[128:131], v[176:179], v[48:51]
	v_mfma_f32_16x16x32_bf16 v[40:43], v[136:139], v[176:179], v[40:43]
	v_mfma_f32_16x16x32_bf16 v[32:35], v[128:131], v[184:187], v[32:35]
	v_mfma_f32_16x16x32_bf16 v[24:27], v[136:139], v[184:187], v[24:27]
	v_mfma_f32_16x16x32_bf16 v[16:19], v[128:131], v[192:195], v[16:19]
	v_mfma_f32_16x16x32_bf16 v[8:11], v[136:139], v[192:195], v[8:11]
	s_add_i32 s74, s74, 2
	s_add_u32 s30, s30, 0x100
	s_addc_u32 s31, s31, 0
	s_add_u32 s72, s72, 0x100
	s_addc_u32 s73, s73, 0
	s_cmp_gt_u32 s74, 29
	v_mfma_f32_16x16x32_bf16 v[60:63], v[132:135], v[172:175], v[60:63]
	v_mfma_f32_16x16x32_bf16 v[56:59], v[140:143], v[172:175], v[56:59]
	v_mfma_f32_16x16x32_bf16 v[48:51], v[132:135], v[180:183], v[48:51]
	v_mfma_f32_16x16x32_bf16 v[40:43], v[140:143], v[180:183], v[40:43]
	v_mfma_f32_16x16x32_bf16 v[32:35], v[132:135], v[188:191], v[32:35]
	v_mfma_f32_16x16x32_bf16 v[24:27], v[140:143], v[188:191], v[24:27]
	v_mfma_f32_16x16x32_bf16 v[16:19], v[132:135], v[196:199], v[16:19]
	v_mfma_f32_16x16x32_bf16 v[8:11], v[140:143], v[196:199], v[8:11]
	v_mfma_f32_16x16x32_bf16 v[52:55], v[200:203], v[160:163], v[52:55]
	v_mfma_f32_16x16x32_bf16 v[44:47], v[208:211], v[160:163], v[44:47]
	v_mfma_f32_16x16x32_bf16 v[36:39], v[200:203], v[176:179], v[36:39]
	v_mfma_f32_16x16x32_bf16 v[28:31], v[208:211], v[176:179], v[28:31]
	v_mfma_f32_16x16x32_bf16 v[20:23], v[200:203], v[184:187], v[20:23]
	v_mfma_f32_16x16x32_bf16 v[12:15], v[208:211], v[184:187], v[12:15]
	v_mfma_f32_16x16x32_bf16 v[4:7], v[200:203], v[192:195], v[4:7]
	v_mfma_f32_16x16x32_bf16 v[0:3], v[208:211], v[192:195], v[0:3]
	v_mfma_f32_16x16x32_bf16 v[52:55], v[204:207], v[172:175], v[52:55]
	v_mfma_f32_16x16x32_bf16 v[44:47], v[212:215], v[172:175], v[44:47]
	v_mfma_f32_16x16x32_bf16 v[36:39], v[204:207], v[180:183], v[36:39]
	v_mfma_f32_16x16x32_bf16 v[28:31], v[212:215], v[180:183], v[28:31]
	v_mfma_f32_16x16x32_bf16 v[20:23], v[204:207], v[188:191], v[20:23]
	v_mfma_f32_16x16x32_bf16 v[12:15], v[212:215], v[188:191], v[12:15]
	v_mfma_f32_16x16x32_bf16 v[4:7], v[204:207], v[196:199], v[4:7]
	v_mfma_f32_16x16x32_bf16 v[0:3], v[212:215], v[196:199], v[0:3]
	s_barrier

; #define PG8_STAGE(bufoff, gbase, voff) do { _Pragma("unroll") for (int _i = 0; _i < 2; ++_i) \
;         __builtin_amdgcn_global_load_lds((const unsigned*)((const char*)(gbase) + (voff)[_i]), (PG8_LAS unsigned*)(lds + (bufoff) + ldsw + _i * 8192), 16, 0, 0); } while (0)
; #define PG8_WAIT_V(n) asm volatile("s_waitcnt vmcnt(" #n ")" ::: "memory")
; template <class Epi, class Sched>
; __device__ __forceinline__ void gemm_phase(PG8_LAS unsigned char* lds, const Gemm g, const Sched& S, const Epi& E) {
;     ...
;     for (;;) {
;         const bool has_next = S.next(ui + 1, nxt);
;         const char* nA = has_next ? (const char*)g.A + (size_t)nxt.pm * tstep : cA; const char* nB = has_next ? (const char*)g.Bt + (size_t)nxt.pn * tstep : cB;
;         for (int t = 0; t < nt; t += 2) {
;             const bool last = (t == nt - 2);
;             const char* a1 = cA + (size_t)(t + 1) * kstep;
;             const char* a2 = last ? nA : cA + (size_t)(t + 2) * kstep; const char* b2 = last ? nB : cB + (size_t)(t + 2) * kstep;
;             const char* a3 = a2 + kstep; const char* b3 = b2 + kstep;
;             if (last && has_next) S.a_ready(nxt);
;             PG8_LDB(B0, 0, 0); PG8_SCHED; PG8_LDA(At, 0, 0); PG8_STAGE(PG8_SA(1, 1), a1 + hstep, voffA);
;             PG8_WAIT_L(8); PG8_BAR; PG8_WAIT_L(0); PG8_MMA(0, 0, At, B0); PG8_BAR; PG8_SCHED;
;             PG8_LDB(B1, 0, 1); PG8_STAGE(PG8_SB(0, 0), b2, voffB);
;             PG8_BAR; PG8_WAIT_L(0); PG8_MMA(0, 1, At, B1); PG8_BAR;
;             PG8_LDA(At, 0, 1); PG8_STAGE(PG8_SA(0, 0), a2, voffA);
;             PG8_BAR; PG8_WAIT_L(0); PG8_MMA(1, 0, At, B0); PG8_BAR; PG8_SCHED;
;             PG8_STAGE(PG8_SB(0, 1), b2 + hstep, voffB);
;             PG8_WAIT_V(6); PG8_BAR; PG8_MMA(1, 1, At, B1); PG8_BAR;
;             PG8_LDB(B0, 1, 0); PG8_SCHED; PG8_LDA(At, 1, 0); PG8_STAGE(PG8_SA(0, 1), a2 + hstep, voffA);
;             PG8_WAIT_L(8); PG8_BAR; PG8_WAIT_L(0); PG8_MMA(0, 0, At, B0); PG8_BAR; PG8_SCHED;
;             PG8_LDB(B1, 1, 1); PG8_STAGE(PG8_SB(1, 0), b3, voffB);
;             PG8_BAR; PG8_WAIT_L(0); PG8_MMA(0, 1, At, B1); PG8_BAR;
;             PG8_LDA(At, 1, 1); PG8_STAGE(PG8_SA(1, 0), a3, voffA);
;             PG8_BAR; PG8_WAIT_L(0); PG8_MMA(1, 0, At, B0); PG8_BAR; PG8_SCHED;
;             PG8_STAGE(PG8_SB(1, 1), b3 + hstep, voffB);
;             PG8_WAIT_V(6); PG8_BAR; PG8_MMA(1, 1, At, B1); PG8_BAR;
.LBB0_802:
	s_ashr_i32 s9, s8, 31
	s_lshl_b64 s[10:11], s[8:9], 20
	v_cmp_lt_i64_e32 vcc, s[16:17], v[140:141]
	s_add_u32 s16, s35, s10
	s_addc_u32 s17, s36, s11
	s_and_b64 s[10:11], vcc, exec
	s_cselect_b32 s9, s17, s27
	s_cselect_b32 s66, s16, s26
	s_ashr_i32 s7, s6, 31
	s_lshl_b64 s[10:11], s[6:7], 20
	s_add_u32 s18, s37, s10
	s_addc_u32 s19, s38, s11
	s_and_b64 s[10:11], vcc, exec
	s_cselect_b32 s7, s19, s29
	s_cselect_b32 s67, s18, s28
	s_add_u32 s26, s26, 0x80080
	s_addc_u32 s27, s27, 0
	s_add_u32 s68, s28, 0x100
	s_addc_u32 s69, s29, 0
	s_mov_b32 s70, -2
	s_setprio 0
	ds_read_b128 v[150:153], v147
	ds_read_b128 v[154:157], v147 offset:1024
	ds_read_b128 v[158:161], v147 offset:2048
	ds_read_b128 v[162:165], v147 offset:3072
	ds_read_b128 v[166:169], v148
	ds_read_b128 v[170:173], v148 offset:1024
	ds_read_b128 v[174:177], v148 offset:2048
	ds_read_b128 v[178:181], v148 offset:3072
	ds_read_b128 v[182:185], v148 offset:4096
	ds_read_b128 v[186:189], v148 offset:5120
	ds_read_b128 v[190:193], v148 offset:6144
	ds_read_b128 v[194:197], v148 offset:7168
	ds_read_b128 v[198:201], v149
	ds_read_b128 v[202:205], v149 offset:1024
	ds_read_b128 v[206:209], v149 offset:2048
	ds_read_b128 v[210:213], v149 offset:3072
	s_add_u32 s10, s26, 0xfff80080
	s_addc_u32 s11, s27, -1
	s_cmp_eq_u32 s70, 28
	s_cselect_b32 s31, s9, s11
	s_cselect_b32 s30, s66, s10
	s_cselect_b32 s29, s7, s69
	s_cselect_b32 s28, s67, s68
	v_lshl_add_u64 v[222:223], s[26:27], 0, v[136:137]
	s_add_i32 m0, s21, 0xc000
	s_nop 0
	global_load_lds_dwordx4 v[222:223], off
	v_lshl_add_u64 v[222:223], s[26:27], 0, v[138:139]
	s_add_i32 m0, s21, 0xe000
	s_nop 0
	global_load_lds_dwordx4 v[222:223], off
	s_waitcnt vmcnt(8)
	s_waitcnt lgkmcnt(0)
	s_setprio 1
	s_barrier
	v_mfma_f32_16x16x32_bf16 v[124:127], v[150:153], v[166:169], 0
	v_mfma_f32_16x16x32_bf16 v[120:123], v[158:161], v[166:169], 0
	v_mfma_f32_16x16x32_bf16 v[108:111], v[150:153], v[174:177], 0
	v_mfma_f32_16x16x32_bf16 v[104:107], v[158:161], v[174:177], 0
	v_mfma_f32_16x16x32_bf16 v[92:95], v[150:153], v[182:185], 0
	v_mfma_f32_16x16x32_bf16 v[88:91], v[158:161], v[182:185], 0
	v_mfma_f32_16x16x32_bf16 v[76:79], v[150:153], v[190:193], 0
	v_mfma_f32_16x16x32_bf16 v[72:75], v[158:161], v[190:193], 0
	v_mfma_f32_16x16x32_bf16 v[124:127], v[154:157], v[170:173], v[124:127]
	v_mfma_f32_16x16x32_bf16 v[120:123], v[162:165], v[170:173], v[120:123]
	v_mfma_f32_16x16x32_bf16 v[108:111], v[154:157], v[178:181], v[108:111]
	v_mfma_f32_16x16x32_bf16 v[104:107], v[162:165], v[178:181], v[104:107]
	v_mfma_f32_16x16x32_bf16 v[92:95], v[154:157], v[186:189], v[92:95]
	v_mfma_f32_16x16x32_bf16 v[88:91], v[162:165], v[186:189], v[88:91]
	v_mfma_f32_16x16x32_bf16 v[76:79], v[154:157], v[194:197], v[76:79]
	v_mfma_f32_16x16x32_bf16 v[72:75], v[162:165], v[194:197], v[72:75]
	v_mfma_f32_16x16x32_bf16 v[116:119], v[198:201], v[166:169], 0
	v_mfma_f32_16x16x32_bf16 v[112:115], v[206:209], v[166:169], 0
	v_mfma_f32_16x16x32_bf16 v[100:103], v[198:201], v[174:177], 0
	v_mfma_f32_16x16x32_bf16 v[96:99], v[206:209], v[174:177], 0
	v_mfma_f32_16x16x32_bf16 v[84:87], v[198:201], v[182:185], 0
	v_mfma_f32_16x16x32_bf16 v[80:83], v[206:209], v[182:185], 0
	v_mfma_f32_16x16x32_bf16 v[68:71], v[198:201], v[190:193], 0
	v_mfma_f32_16x16x32_bf16 v[64:67], v[206:209], v[190:193], 0
	v_mfma_f32_16x16x32_bf16 v[116:119], v[202:205], v[170:173], v[116:119]
	v_mfma_f32_16x16x32_bf16 v[112:115], v[210:213], v[170:173], v[112:115]
	v_mfma_f32_16x16x32_bf16 v[100:103], v[202:205], v[178:181], v[100:103]
	v_mfma_f32_16x16x32_bf16 v[96:99], v[210:213], v[178:181], v[96:99]
	v_mfma_f32_16x16x32_bf16 v[84:87], v[202:205], v[186:189], v[84:87]
	v_mfma_f32_16x16x32_bf16 v[80:83], v[210:213], v[186:189], v[80:83]
	v_mfma_f32_16x16x32_bf16 v[68:71], v[202:205], v[194:197], v[68:71]
	v_mfma_f32_16x16x32_bf16 v[64:67], v[210:213], v[194:197], v[64:67]
	s_barrier
	s_setprio 0
	ds_read_b128 v[166:169], v148 offset:16384
	ds_read_b128 v[170:173], v148 offset:17408
	ds_read_b128 v[174:177], v148 offset:18432
	ds_read_b128 v[178:181], v148 offset:19456
	ds_read_b128 v[182:185], v148 offset:20480
	ds_read_b128 v[186:189], v148 offset:21504
	ds_read_b128 v[190:193], v148 offset:22528
	ds_read_b128 v[194:197], v148 offset:23552
	s_add_i32 s10, s50, s39
	v_lshl_add_u64 v[214:215], s[28:29], 0, v[132:133]
	s_mov_b32 m0, s10
	s_nop 0
	global_load_lds_dwordx4 v[214:215], off
	v_lshl_add_u64 v[216:217], s[28:29], 0, v[128:129]
	s_add_i32 m0, s10, 0x2000
	s_nop 0
	global_load_lds_dwordx4 v[216:217], off
	s_mov_b32 m0, s21
	v_lshl_add_u64 v[218:219], s[30:31], 0, v[134:135]
	global_load_lds_dwordx4 v[218:219], off
	v_lshl_add_u64 v[220:221], s[30:31], 0, v[130:131]
	s_mov_b32 m0, s42
	s_nop 0
	global_load_lds_dwordx4 v[220:221], off
	s_add_u32 s10, s28, 0x80000
	s_addc_u32 s11, s29, 0
	s_add_i32 s33, s51, s39
	v_lshl_add_u64 v[222:223], s[10:11], 0, v[132:133]
	s_mov_b32 m0, s33
	s_nop 0
	global_load_lds_dwordx4 v[222:223], off
	v_lshl_add_u64 v[222:223], s[10:11], 0, v[128:129]
	s_add_i32 m0, s33, 0x2000
	s_nop 0
	global_load_lds_dwordx4 v[222:223], off
	s_waitcnt vmcnt(8)
	s_waitcnt lgkmcnt(0)
	s_setprio 1
	s_barrier
; #define PG8_STAGE(bufoff, gbase, voff) do { _Pragma("unroll") for (int _i = 0; _i < 2; ++_i) \
;         __builtin_amdgcn_global_load_lds((const unsigned*)((const char*)(gbase) + (voff)[_i]), (PG8_LAS unsigned*)(lds + (bufoff) + ldsw + _i * 8192), 16, 0, 0); } while (0)
; #define PG8_LDA(dst, b, h) do { _Pragma("unroll") for (int m = 0; m < 4; ++m) _Pragma("unroll") for (int k = 0; k < 2; ++k) dst[m][k] = *(const PG8_LAS bf16x8*)(lds + PG8_SA(b, h) + aoff + m * 2048 + k * 1024); } while (0)
; #define PG8_LDB(dst, b, h) do { _Pragma("unroll") for (int n = 0; n < 2; ++n) _Pragma("unroll") for (int k = 0; k < 2; ++k) dst[n][k] = *(const PG8_LAS bf16x8*)(lds + PG8_SB(b, h) + boff + n * 2048 + k * 1024); } while (0)
; #define PG8_WAIT_V(n) asm volatile("s_waitcnt vmcnt(" #n ")" ::: "memory")
; #define PG8_WAIT_L(n) asm volatile("s_waitcnt lgkmcnt(" #n ")" ::: "memory")
; #define PG8_BAR __builtin_amdgcn_s_barrier()
; #define PG8_SCHED __builtin_amdgcn_sched_barrier(0)
; template <class Epi, class Sched>
; __device__ __forceinline__ void gemm_phase(PG8_LAS unsigned char* lds, const Gemm g, const Sched& S, const Epi& E) {
;     ...
;             PG8_LDB(B0, 0, 0); PG8_SCHED; PG8_LDA(At, 0, 0); PG8_STAGE(PG8_SA(1, 1), a1 + hstep, voffA);
;             PG8_WAIT_L(8); PG8_BAR; PG8_WAIT_L(0); PG8_MMA(0, 0, At, B0); PG8_BAR; PG8_SCHED;
;             PG8_LDB(B1, 0, 1); PG8_STAGE(PG8_SB(0, 0), b2, voffB);
;             PG8_BAR; PG8_WAIT_L(0); PG8_MMA(0, 1, At, B1); PG8_BAR;
;             PG8_LDA(At, 0, 1); PG8_STAGE(PG8_SA(0, 0), a2, voffA);
;             PG8_BAR; PG8_WAIT_L(0); PG8_MMA(1, 0, At, B0); PG8_BAR; PG8_SCHED;
;             PG8_STAGE(PG8_SB(0, 1), b2 + hstep, voffB);
;             PG8_WAIT_V(6); PG8_BAR; PG8_MMA(1, 1, At, B1); PG8_BAR;
;             PG8_LDB(B0, 1, 0); PG8_SCHED; PG8_LDA(At, 1, 0); PG8_STAGE(PG8_SA(0, 1), a2 + hstep, voffA);
;             PG8_WAIT_L(8); PG8_BAR; PG8_WAIT_L(0); PG8_MMA(0, 0, At, B0); PG8_BAR; PG8_SCHED;
;             PG8_LDB(B1, 1, 1); PG8_STAGE(PG8_SB(1, 0), b3, voffB);
;             PG8_BAR; PG8_WAIT_L(0); PG8_MMA(0, 1, At, B1); PG8_BAR;
;             PG8_LDA(At, 1, 1); PG8_STAGE(PG8_SA(1, 0), a3, voffA);
;             PG8_BAR; PG8_WAIT_L(0); PG8_MMA(1, 0, At, B0); PG8_BAR; PG8_SCHED;
;             PG8_STAGE(PG8_SB(1, 1), b3 + hstep, voffB);
;             PG8_WAIT_V(6); PG8_BAR; PG8_MMA(1, 1, At, B1); PG8_BAR;
	v_mfma_f32_16x16x32_bf16 v[60:63], v[150:153], v[166:169], 0
	v_mfma_f32_16x16x32_bf16 v[56:59], v[158:161], v[166:169], 0
	v_mfma_f32_16x16x32_bf16 v[44:47], v[150:153], v[174:177], 0
	v_mfma_f32_16x16x32_bf16 v[40:43], v[158:161], v[174:177], 0
	v_mfma_f32_16x16x32_bf16 v[28:31], v[150:153], v[182:185], 0
	v_mfma_f32_16x16x32_bf16 v[24:27], v[158:161], v[182:185], 0
	v_mfma_f32_16x16x32_bf16 v[12:15], v[150:153], v[190:193], 0
	v_mfma_f32_16x16x32_bf16 v[8:11], v[158:161], v[190:193], 0
	s_add_i32 s33, 0, 0x18000
	v_mfma_f32_16x16x32_bf16 v[60:63], v[154:157], v[170:173], v[60:63]
	v_mfma_f32_16x16x32_bf16 v[56:59], v[162:165], v[170:173], v[56:59]
	v_mfma_f32_16x16x32_bf16 v[44:47], v[154:157], v[178:181], v[44:47]
	v_mfma_f32_16x16x32_bf16 v[40:43], v[162:165], v[178:181], v[40:43]
	v_mfma_f32_16x16x32_bf16 v[28:31], v[154:157], v[186:189], v[28:31]
	v_mfma_f32_16x16x32_bf16 v[24:27], v[162:165], v[186:189], v[24:27]
	v_mfma_f32_16x16x32_bf16 v[12:15], v[154:157], v[194:197], v[12:15]
	v_mfma_f32_16x16x32_bf16 v[8:11], v[162:165], v[194:197], v[8:11]
	v_mfma_f32_16x16x32_bf16 v[52:55], v[198:201], v[166:169], 0
	v_mfma_f32_16x16x32_bf16 v[48:51], v[206:209], v[166:169], 0
	v_mfma_f32_16x16x32_bf16 v[36:39], v[198:201], v[174:177], 0
	v_mfma_f32_16x16x32_bf16 v[32:35], v[206:209], v[174:177], 0
	v_mfma_f32_16x16x32_bf16 v[20:23], v[198:201], v[182:185], 0
	v_mfma_f32_16x16x32_bf16 v[16:19], v[206:209], v[182:185], 0
	v_mfma_f32_16x16x32_bf16 v[4:7], v[198:201], v[190:193], 0
	v_mfma_f32_16x16x32_bf16 v[0:3], v[206:209], v[190:193], 0
	v_mfma_f32_16x16x32_bf16 v[52:55], v[202:205], v[170:173], v[52:55]
	v_mfma_f32_16x16x32_bf16 v[48:51], v[210:213], v[170:173], v[48:51]
	v_mfma_f32_16x16x32_bf16 v[36:39], v[202:205], v[178:181], v[36:39]
	v_mfma_f32_16x16x32_bf16 v[32:35], v[210:213], v[178:181], v[32:35]
	v_mfma_f32_16x16x32_bf16 v[20:23], v[202:205], v[186:189], v[20:23]
	v_mfma_f32_16x16x32_bf16 v[16:19], v[210:213], v[186:189], v[16:19]
	v_mfma_f32_16x16x32_bf16 v[4:7], v[202:205], v[194:197], v[4:7]
	v_mfma_f32_16x16x32_bf16 v[0:3], v[210:213], v[194:197], v[0:3]
	s_barrier
	s_setprio 0
	ds_read_b128 v[150:153], v147 offset:32768
	ds_read_b128 v[154:157], v147 offset:33792
	ds_read_b128 v[158:161], v147 offset:34816
	ds_read_b128 v[162:165], v147 offset:35840
	ds_read_b128 v[166:169], v148 offset:32768
	ds_read_b128 v[170:173], v148 offset:33792
	ds_read_b128 v[174:177], v148 offset:34816
	ds_read_b128 v[178:181], v148 offset:35840
	ds_read_b128 v[182:185], v148 offset:36864
	ds_read_b128 v[186:189], v148 offset:37888
	ds_read_b128 v[190:193], v148 offset:38912
	ds_read_b128 v[194:197], v148 offset:39936
	ds_read_b128 v[198:201], v149 offset:32768
	ds_read_b128 v[202:205], v149 offset:33792
	ds_read_b128 v[206:209], v149 offset:34816
	ds_read_b128 v[210:213], v149 offset:35840
	s_add_u32 s10, s30, 0x80000
	s_addc_u32 s11, s31, 0
	s_mov_b32 m0, s43
	v_lshl_add_u64 v[222:223], s[10:11], 0, v[134:135]
	global_load_lds_dwordx4 v[222:223], off
	v_lshl_add_u64 v[222:223], s[10:11], 0, v[130:131]
	s_mov_b32 m0, s44
	s_nop 0
	global_load_lds_dwordx4 v[222:223], off
	s_waitcnt vmcnt(8)
	s_waitcnt lgkmcnt(0)
	s_setprio 1
	s_barrier
	v_mfma_f32_16x16x32_bf16 v[124:127], v[150:153], v[166:169], v[124:127]
	v_mfma_f32_16x16x32_bf16 v[120:123], v[158:161], v[166:169], v[120:123]
	v_mfma_f32_16x16x32_bf16 v[108:111], v[150:153], v[174:177], v[108:111]
	v_mfma_f32_16x16x32_bf16 v[104:107], v[158:161], v[174:177], v[104:107]
	v_mfma_f32_16x16x32_bf16 v[92:95], v[150:153], v[182:185], v[92:95]
	v_mfma_f32_16x16x32_bf16 v[88:91], v[158:161], v[182:185], v[88:91]
	v_mfma_f32_16x16x32_bf16 v[76:79], v[150:153], v[190:193], v[76:79]
	v_mfma_f32_16x16x32_bf16 v[72:75], v[158:161], v[190:193], v[72:75]
	v_mfma_f32_16x16x32_bf16 v[124:127], v[154:157], v[170:173], v[124:127]
	v_mfma_f32_16x16x32_bf16 v[120:123], v[162:165], v[170:173], v[120:123]
	v_mfma_f32_16x16x32_bf16 v[108:111], v[154:157], v[178:181], v[108:111]
	v_mfma_f32_16x16x32_bf16 v[104:107], v[162:165], v[178:181], v[104:107]
	v_mfma_f32_16x16x32_bf16 v[92:95], v[154:157], v[186:189], v[92:95]
	v_mfma_f32_16x16x32_bf16 v[88:91], v[162:165], v[186:189], v[88:91]
	v_mfma_f32_16x16x32_bf16 v[76:79], v[154:157], v[194:197], v[76:79]
	v_mfma_f32_16x16x32_bf16 v[72:75], v[162:165], v[194:197], v[72:75]
	v_mfma_f32_16x16x32_bf16 v[116:119], v[198:201], v[166:169], v[116:119]
	v_mfma_f32_16x16x32_bf16 v[112:115], v[206:209], v[166:169], v[112:115]
	v_mfma_f32_16x16x32_bf16 v[100:103], v[198:201], v[174:177], v[100:103]
	v_mfma_f32_16x16x32_bf16 v[96:99], v[206:209], v[174:177], v[96:99]
	v_mfma_f32_16x16x32_bf16 v[84:87], v[198:201], v[182:185], v[84:87]
	v_mfma_f32_16x16x32_bf16 v[80:83], v[206:209], v[182:185], v[80:83]
	v_mfma_f32_16x16x32_bf16 v[68:71], v[198:201], v[190:193], v[68:71]
	v_mfma_f32_16x16x32_bf16 v[64:67], v[206:209], v[190:193], v[64:67]
	v_mfma_f32_16x16x32_bf16 v[116:119], v[202:205], v[170:173], v[116:119]
	v_mfma_f32_16x16x32_bf16 v[112:115], v[210:213], v[170:173], v[112:115]
	v_mfma_f32_16x16x32_bf16 v[100:103], v[202:205], v[178:181], v[100:103]
	v_mfma_f32_16x16x32_bf16 v[96:99], v[210:213], v[178:181], v[96:99]
	v_mfma_f32_16x16x32_bf16 v[84:87], v[202:205], v[186:189], v[84:87]
	v_mfma_f32_16x16x32_bf16 v[80:83], v[210:213], v[186:189], v[80:83]
	v_mfma_f32_16x16x32_bf16 v[68:71], v[202:205], v[194:197], v[68:71]
	v_mfma_f32_16x16x32_bf16 v[64:67], v[210:213], v[194:197], v[64:67]
	s_barrier
; #define PG8_STAGE(bufoff, gbase, voff) do { _Pragma("unroll") for (int _i = 0; _i < 2; ++_i) \
;         __builtin_amdgcn_global_load_lds((const unsigned*)((const char*)(gbase) + (voff)[_i]), (PG8_LAS unsigned*)(lds + (bufoff) + ldsw + _i * 8192), 16, 0, 0); } while (0)
; #define PG8_LDA(dst, b, h) do { _Pragma("unroll") for (int m = 0; m < 4; ++m) _Pragma("unroll") for (int k = 0; k < 2; ++k) dst[m][k] = *(const PG8_LAS bf16x8*)(lds + PG8_SA(b, h) + aoff + m * 2048 + k * 1024); } while (0)
; #define PG8_LDB(dst, b, h) do { _Pragma("unroll") for (int n = 0; n < 2; ++n) _Pragma("unroll") for (int k = 0; k < 2; ++k) dst[n][k] = *(const PG8_LAS bf16x8*)(lds + PG8_SB(b, h) + boff + n * 2048 + k * 1024); } while (0)
; #define PG8_WAIT_V(n) asm volatile("s_waitcnt vmcnt(" #n ")" ::: "memory")
; #define PG8_WAIT_L(n) asm volatile("s_waitcnt lgkmcnt(" #n ")" ::: "memory")
; #define PG8_BAR __builtin_amdgcn_s_barrier()
; #define PG8_SCHED __builtin_amdgcn_sched_barrier(0)
; template <class Epi, class Sched>
; __device__ __forceinline__ void gemm_phase(PG8_LAS unsigned char* lds, const Gemm g, const Sched& S, const Epi& E) {
;     ...
;             PG8_LDB(B0, 0, 0); PG8_SCHED; PG8_LDA(At, 0, 0); PG8_STAGE(PG8_SA(1, 1), a1 + hstep, voffA);
;             PG8_WAIT_L(8); PG8_BAR; PG8_WAIT_L(0); PG8_MMA(0, 0, At, B0); PG8_BAR; PG8_SCHED;
;             PG8_LDB(B1, 0, 1); PG8_STAGE(PG8_SB(0, 0), b2, voffB);
;             PG8_BAR; PG8_WAIT_L(0); PG8_MMA(0, 1, At, B1); PG8_BAR;
;             PG8_LDA(At, 0, 1); PG8_STAGE(PG8_SA(0, 0), a2, voffA);
;             PG8_BAR; PG8_WAIT_L(0); PG8_MMA(1, 0, At, B0); PG8_BAR; PG8_SCHED;
;             PG8_STAGE(PG8_SB(0, 1), b2 + hstep, voffB);
;             PG8_WAIT_V(6); PG8_BAR; PG8_MMA(1, 1, At, B1); PG8_BAR;
;             PG8_LDB(B0, 1, 0); PG8_SCHED; PG8_LDA(At, 1, 0); PG8_STAGE(PG8_SA(0, 1), a2 + hstep, voffA);
;             PG8_WAIT_L(8); PG8_BAR; PG8_WAIT_L(0); PG8_MMA(0, 0, At, B0); PG8_BAR; PG8_SCHED;
;             PG8_LDB(B1, 1, 1); PG8_STAGE(PG8_SB(1, 0), b3, voffB);
;             PG8_BAR; PG8_WAIT_L(0); PG8_MMA(0, 1, At, B1); PG8_BAR;
;             PG8_LDA(At, 1, 1); PG8_STAGE(PG8_SA(1, 0), a3, voffA);
;             PG8_BAR; PG8_WAIT_L(0); PG8_MMA(1, 0, At, B0); PG8_BAR; PG8_SCHED;
;             PG8_STAGE(PG8_SB(1, 1), b3 + hstep, voffB);
;             PG8_WAIT_V(6); PG8_BAR; PG8_MMA(1, 1, At, B1); PG8_BAR;
;         }
	s_setprio 0
	ds_read_b128 v[166:169], v148 offset:49152
	ds_read_b128 v[170:173], v148 offset:50176
	ds_read_b128 v[174:177], v148 offset:51200
	ds_read_b128 v[178:181], v148 offset:52224
	ds_read_b128 v[182:185], v148 offset:53248
	ds_read_b128 v[186:189], v148 offset:54272
	ds_read_b128 v[190:193], v148 offset:55296
	ds_read_b128 v[194:197], v148 offset:56320
	s_add_i32 s30, 0, 0x1c000
	s_add_i32 s10, s33, s39
	v_lshl_add_u64 v[214:215], v[214:215], 0, s[4:5]
	s_mov_b32 m0, s10
	s_nop 0
	global_load_lds_dwordx4 v[214:215], off
	v_lshl_add_u64 v[214:215], v[216:217], 0, s[4:5]
	s_add_i32 m0, s10, 0x2000
	s_nop 0
	global_load_lds_dwordx4 v[214:215], off
	s_mov_b32 m0, s46
	v_lshl_add_u64 v[214:215], v[218:219], 0, s[4:5]
	global_load_lds_dwordx4 v[214:215], off
	v_lshl_add_u64 v[214:215], v[220:221], 0, s[4:5]
	s_mov_b32 m0, s47
	s_nop 0
	global_load_lds_dwordx4 v[214:215], off
	s_add_u32 s10, s28, 0x80080
	s_addc_u32 s11, s29, 0
	s_add_i32 s28, s30, s39
	v_lshl_add_u64 v[222:223], s[10:11], 0, v[132:133]
	s_mov_b32 m0, s28
	s_nop 0
	global_load_lds_dwordx4 v[222:223], off
	v_lshl_add_u64 v[222:223], s[10:11], 0, v[128:129]
	s_add_i32 m0, s28, 0x2000
	s_nop 0
	global_load_lds_dwordx4 v[222:223], off
	s_waitcnt vmcnt(8)
	s_waitcnt lgkmcnt(0)
	s_setprio 1
	s_barrier
	v_mfma_f32_16x16x32_bf16 v[60:63], v[150:153], v[166:169], v[60:63]
	v_mfma_f32_16x16x32_bf16 v[56:59], v[158:161], v[166:169], v[56:59]
	v_mfma_f32_16x16x32_bf16 v[44:47], v[150:153], v[174:177], v[44:47]
	v_mfma_f32_16x16x32_bf16 v[40:43], v[158:161], v[174:177], v[40:43]
	v_mfma_f32_16x16x32_bf16 v[28:31], v[150:153], v[182:185], v[28:31]
	v_mfma_f32_16x16x32_bf16 v[24:27], v[158:161], v[182:185], v[24:27]
	v_mfma_f32_16x16x32_bf16 v[12:15], v[150:153], v[190:193], v[12:15]
	v_mfma_f32_16x16x32_bf16 v[8:11], v[158:161], v[190:193], v[8:11]
	s_add_i32 s70, s70, 2
	s_add_u32 s26, s26, 0x100
	s_addc_u32 s27, s27, 0
	s_add_u32 s68, s68, 0x100
	s_addc_u32 s69, s69, 0
	s_cmp_gt_u32 s70, 29
	v_mfma_f32_16x16x32_bf16 v[60:63], v[154:157], v[170:173], v[60:63]
	v_mfma_f32_16x16x32_bf16 v[56:59], v[162:165], v[170:173], v[56:59]
	v_mfma_f32_16x16x32_bf16 v[44:47], v[154:157], v[178:181], v[44:47]
	v_mfma_f32_16x16x32_bf16 v[40:43], v[162:165], v[178:181], v[40:43]
	v_mfma_f32_16x16x32_bf16 v[28:31], v[154:157], v[186:189], v[28:31]
	v_mfma_f32_16x16x32_bf16 v[24:27], v[162:165], v[186:189], v[24:27]
	v_mfma_f32_16x16x32_bf16 v[12:15], v[154:157], v[194:197], v[12:15]
	v_mfma_f32_16x16x32_bf16 v[8:11], v[162:165], v[194:197], v[8:11]
	v_mfma_f32_16x16x32_bf16 v[52:55], v[198:201], v[166:169], v[52:55]
	v_mfma_f32_16x16x32_bf16 v[48:51], v[206:209], v[166:169], v[48:51]
	v_mfma_f32_16x16x32_bf16 v[36:39], v[198:201], v[174:177], v[36:39]
	v_mfma_f32_16x16x32_bf16 v[32:35], v[206:209], v[174:177], v[32:35]
	v_mfma_f32_16x16x32_bf16 v[20:23], v[198:201], v[182:185], v[20:23]
	v_mfma_f32_16x16x32_bf16 v[16:19], v[206:209], v[182:185], v[16:19]
	v_mfma_f32_16x16x32_bf16 v[4:7], v[198:201], v[190:193], v[4:7]
	v_mfma_f32_16x16x32_bf16 v[0:3], v[206:209], v[190:193], v[0:3]
	v_mfma_f32_16x16x32_bf16 v[52:55], v[202:205], v[170:173], v[52:55]
	v_mfma_f32_16x16x32_bf16 v[48:51], v[210:213], v[170:173], v[48:51]
	v_mfma_f32_16x16x32_bf16 v[36:39], v[202:205], v[178:181], v[36:39]
	v_mfma_f32_16x16x32_bf16 v[32:35], v[210:213], v[178:181], v[32:35]
	v_mfma_f32_16x16x32_bf16 v[20:23], v[202:205], v[186:189], v[20:23]
	v_mfma_f32_16x16x32_bf16 v[16:19], v[210:213], v[186:189], v[16:19]
	v_mfma_f32_16x16x32_bf16 v[4:7], v[202:205], v[194:197], v[4:7]
	v_mfma_f32_16x16x32_bf16 v[0:3], v[210:213], v[194:197], v[0:3]
	s_barrier

; #define PG8_STAGE(bufoff, gbase, voff) do { _Pragma("unroll") for (int _i = 0; _i < 2; ++_i) \
;         __builtin_amdgcn_global_load_lds((const unsigned*)((const char*)(gbase) + (voff)[_i]), (PG8_LAS unsigned*)(lds + (bufoff) + ldsw + _i * 8192), 16, 0, 0); } while (0)
; #define PG8_WAIT_V(n) asm volatile("s_waitcnt vmcnt(" #n ")" ::: "memory")
; template <class Epi, class Sched>
; __device__ __forceinline__ void gemm_phase(PG8_LAS unsigned char* lds, const Gemm g, const Sched& S, const Epi& E) {
;     ...
;         const bool has_next = S.next(ui + 1, nxt);
;         const char* nA = has_next ? (const char*)g.A + (size_t)nxt.pm * tstep : cA; const char* nB = has_next ? (const char*)g.Bt + (size_t)nxt.pn * tstep : cB;
;         for (int t = 0; t < nt; t += 2) {
;             const bool last = (t == nt - 2);
;             const char* a1 = cA + (size_t)(t + 1) * kstep;
;             const char* a2 = last ? nA : cA + (size_t)(t + 2) * kstep; const char* b2 = last ? nB : cB + (size_t)(t + 2) * kstep;
;             const char* a3 = a2 + kstep; const char* b3 = b2 + kstep;
;             if (last && has_next) S.a_ready(nxt);
;             PG8_LDB(B0, 0, 0); PG8_SCHED; PG8_LDA(At, 0, 0); PG8_STAGE(PG8_SA(1, 1), a1 + hstep, voffA);
;             PG8_WAIT_L(8); PG8_BAR; PG8_WAIT_L(0); PG8_MMA(0, 0, At, B0); PG8_BAR; PG8_SCHED;
;             PG8_LDB(B1, 0, 1); PG8_STAGE(PG8_SB(0, 0), b2, voffB);
;             PG8_BAR; PG8_WAIT_L(0); PG8_MMA(0, 1, At, B1); PG8_BAR;
;             PG8_LDA(At, 0, 1); PG8_STAGE(PG8_SA(0, 0), a2, voffA);
;             PG8_BAR; PG8_WAIT_L(0); PG8_MMA(1, 0, At, B0); PG8_BAR; PG8_SCHED;
;             PG8_STAGE(PG8_SB(0, 1), b2 + hstep, voffB);
;             PG8_WAIT_V(6); PG8_BAR; PG8_MMA(1, 1, At, B1); PG8_BAR;
;             PG8_LDB(B0, 1, 0); PG8_SCHED; PG8_LDA(At, 1, 0); PG8_STAGE(PG8_SA(0, 1), a2 + hstep, voffA);
;             PG8_WAIT_L(8); PG8_BAR; PG8_WAIT_L(0); PG8_MMA(0, 0, At, B0); PG8_BAR; PG8_SCHED;
;             PG8_LDB(B1, 1, 1); PG8_STAGE(PG8_SB(1, 0), b3, voffB);
;             PG8_BAR; PG8_WAIT_L(0); PG8_MMA(0, 1, At, B1); PG8_BAR;
;             PG8_LDA(At, 1, 1); PG8_STAGE(PG8_SA(1, 0), a3, voffA);
;             PG8_BAR; PG8_WAIT_L(0); PG8_MMA(1, 0, At, B0); PG8_BAR; PG8_SCHED;
;             PG8_STAGE(PG8_SB(1, 1), b3 + hstep, voffB);
;             PG8_WAIT_V(6); PG8_BAR; PG8_MMA(1, 1, At, B1); PG8_BAR;
.LBB0_881:
	s_add_u32 s26, s26, 0x160080
	s_addc_u32 s27, s27, 0
	s_add_u32 s67, s28, 0x100
	s_addc_u32 s68, s29, 0
	s_mov_b32 s69, -2
	s_setprio 0
	ds_read_b128 v[108:111], v247
	ds_read_b128 v[112:115], v247 offset:1024
	ds_read_b128 v[124:127], v247 offset:2048
	ds_read_b128 v[128:131], v247 offset:3072
	ds_read_b128 v[144:147], v248
	ds_read_b128 v[148:151], v248 offset:1024
	ds_read_b128 v[152:155], v248 offset:2048
	ds_read_b128 v[156:159], v248 offset:3072
	ds_read_b128 v[160:163], v248 offset:4096
	ds_read_b128 v[164:167], v248 offset:5120
	ds_read_b128 v[168:171], v248 offset:6144
	ds_read_b128 v[172:175], v248 offset:7168
	ds_read_b128 v[188:191], v249
	ds_read_b128 v[192:195], v249 offset:1024
	ds_read_b128 v[196:199], v249 offset:2048
	ds_read_b128 v[200:203], v249 offset:3072
	s_add_u32 s10, s26, 0xffea0080
	s_addc_u32 s11, s27, -1
	s_cmpk_eq_i32 s69, 0x54
	s_cselect_b32 s31, s1, s11
	s_cselect_b32 s30, s0, s10
	s_cselect_b32 s29, s5, s68
	s_cselect_b32 s28, s4, s67
	v_lshl_add_u64 v[252:253], s[26:27], 0, v[184:185]
	s_add_i32 m0, s40, 0xc000
	s_nop 0
	global_load_lds_dwordx4 v[252:253], off
	v_lshl_add_u64 v[252:253], s[26:27], 0, v[186:187]
	s_add_i32 m0, s40, 0xe000
	s_nop 0
	global_load_lds_dwordx4 v[252:253], off
	s_waitcnt vmcnt(8)
	s_waitcnt lgkmcnt(0)
	s_setprio 1
	s_barrier
	v_mfma_f32_16x16x32_bf16 v[140:143], v[108:111], v[144:147], 0
	v_mfma_f32_16x16x32_bf16 v[136:139], v[124:127], v[144:147], 0
	v_mfma_f32_16x16x32_bf16 v[116:119], v[108:111], v[152:155], 0
	v_mfma_f32_16x16x32_bf16 v[104:107], v[124:127], v[152:155], 0
	v_mfma_f32_16x16x32_bf16 v[92:95], v[108:111], v[160:163], 0
	v_mfma_f32_16x16x32_bf16 v[88:91], v[124:127], v[160:163], 0
	v_mfma_f32_16x16x32_bf16 v[76:79], v[108:111], v[168:171], 0
	v_mfma_f32_16x16x32_bf16 v[72:75], v[124:127], v[168:171], 0
	v_mfma_f32_16x16x32_bf16 v[140:143], v[112:115], v[148:151], v[140:143]
	v_mfma_f32_16x16x32_bf16 v[136:139], v[128:131], v[148:151], v[136:139]
	v_mfma_f32_16x16x32_bf16 v[116:119], v[112:115], v[156:159], v[116:119]
	v_mfma_f32_16x16x32_bf16 v[104:107], v[128:131], v[156:159], v[104:107]
	v_mfma_f32_16x16x32_bf16 v[92:95], v[112:115], v[164:167], v[92:95]
	v_mfma_f32_16x16x32_bf16 v[88:91], v[128:131], v[164:167], v[88:91]
	v_mfma_f32_16x16x32_bf16 v[76:79], v[112:115], v[172:175], v[76:79]
	v_mfma_f32_16x16x32_bf16 v[72:75], v[128:131], v[172:175], v[72:75]
	v_mfma_f32_16x16x32_bf16 v[132:135], v[188:191], v[144:147], 0
	v_mfma_f32_16x16x32_bf16 v[120:123], v[196:199], v[144:147], 0
	v_mfma_f32_16x16x32_bf16 v[100:103], v[188:191], v[152:155], 0
	v_mfma_f32_16x16x32_bf16 v[96:99], v[196:199], v[152:155], 0
	v_mfma_f32_16x16x32_bf16 v[84:87], v[188:191], v[160:163], 0
	v_mfma_f32_16x16x32_bf16 v[80:83], v[196:199], v[160:163], 0
	v_mfma_f32_16x16x32_bf16 v[68:71], v[188:191], v[168:171], 0
	v_mfma_f32_16x16x32_bf16 v[64:67], v[196:199], v[168:171], 0
	v_mfma_f32_16x16x32_bf16 v[132:135], v[192:195], v[148:151], v[132:135]
	v_mfma_f32_16x16x32_bf16 v[120:123], v[200:203], v[148:151], v[120:123]
	v_mfma_f32_16x16x32_bf16 v[100:103], v[192:195], v[156:159], v[100:103]
	v_mfma_f32_16x16x32_bf16 v[96:99], v[200:203], v[156:159], v[96:99]
	v_mfma_f32_16x16x32_bf16 v[84:87], v[192:195], v[164:167], v[84:87]
	v_mfma_f32_16x16x32_bf16 v[80:83], v[200:203], v[164:167], v[80:83]
	v_mfma_f32_16x16x32_bf16 v[68:71], v[192:195], v[172:175], v[68:71]
	v_mfma_f32_16x16x32_bf16 v[64:67], v[200:203], v[172:175], v[64:67]
	s_barrier
	s_setprio 0
	ds_read_b128 v[144:147], v248 offset:16384
	ds_read_b128 v[148:151], v248 offset:17408
	ds_read_b128 v[152:155], v248 offset:18432
	ds_read_b128 v[156:159], v248 offset:19456
	ds_read_b128 v[160:163], v248 offset:20480
	ds_read_b128 v[164:167], v248 offset:21504
	ds_read_b128 v[168:171], v248 offset:22528
	ds_read_b128 v[172:175], v248 offset:23552
	s_add_i32 s10, s49, s39
	v_lshl_add_u64 v[204:205], s[28:29], 0, v[178:179]
	s_mov_b32 m0, s10
	s_nop 0
	global_load_lds_dwordx4 v[204:205], off
	v_lshl_add_u64 v[206:207], s[28:29], 0, v[182:183]
	s_add_i32 m0, s10, 0x2000
	s_nop 0
	global_load_lds_dwordx4 v[206:207], off
	s_mov_b32 m0, s40
	v_lshl_add_u64 v[208:209], s[30:31], 0, v[176:177]
	global_load_lds_dwordx4 v[208:209], off
	v_lshl_add_u64 v[210:211], s[30:31], 0, v[180:181]
	s_mov_b32 m0, s41
	s_nop 0
	global_load_lds_dwordx4 v[210:211], off
	s_add_u32 s10, s28, 0x160000
	s_addc_u32 s11, s29, 0
	s_add_i32 s33, s50, s39
	v_lshl_add_u64 v[252:253], s[10:11], 0, v[178:179]
	s_mov_b32 m0, s33
	s_nop 0
	global_load_lds_dwordx4 v[252:253], off
	v_lshl_add_u64 v[252:253], s[10:11], 0, v[182:183]
	s_add_i32 m0, s33, 0x2000
	s_nop 0
	global_load_lds_dwordx4 v[252:253], off
	s_waitcnt vmcnt(8)
	s_waitcnt lgkmcnt(0)
	s_setprio 1
	s_barrier
; #define PG8_STAGE(bufoff, gbase, voff) do { _Pragma("unroll") for (int _i = 0; _i < 2; ++_i) \
;         __builtin_amdgcn_global_load_lds((const unsigned*)((const char*)(gbase) + (voff)[_i]), (PG8_LAS unsigned*)(lds + (bufoff) + ldsw + _i * 8192), 16, 0, 0); } while (0)
; #define PG8_LDA(dst, b, h) do { _Pragma("unroll") for (int m = 0; m < 4; ++m) _Pragma("unroll") for (int k = 0; k < 2; ++k) dst[m][k] = *(const PG8_LAS bf16x8*)(lds + PG8_SA(b, h) + aoff + m * 2048 + k * 1024); } while (0)
; #define PG8_LDB(dst, b, h) do { _Pragma("unroll") for (int n = 0; n < 2; ++n) _Pragma("unroll") for (int k = 0; k < 2; ++k) dst[n][k] = *(const PG8_LAS bf16x8*)(lds + PG8_SB(b, h) + boff + n * 2048 + k * 1024); } while (0)
; #define PG8_WAIT_V(n) asm volatile("s_waitcnt vmcnt(" #n ")" ::: "memory")
; #define PG8_WAIT_L(n) asm volatile("s_waitcnt lgkmcnt(" #n ")" ::: "memory")
; #define PG8_BAR __builtin_amdgcn_s_barrier()
; #define PG8_SCHED __builtin_amdgcn_sched_barrier(0)
; template <class Epi, class Sched>
; __device__ __forceinline__ void gemm_phase(PG8_LAS unsigned char* lds, const Gemm g, const Sched& S, const Epi& E) {
;     ...
;             PG8_LDB(B0, 0, 0); PG8_SCHED; PG8_LDA(At, 0, 0); PG8_STAGE(PG8_SA(1, 1), a1 + hstep, voffA);
;             PG8_WAIT_L(8); PG8_BAR; PG8_WAIT_L(0); PG8_MMA(0, 0, At, B0); PG8_BAR; PG8_SCHED;
;             PG8_LDB(B1, 0, 1); PG8_STAGE(PG8_SB(0, 0), b2, voffB);
;             PG8_BAR; PG8_WAIT_L(0); PG8_MMA(0, 1, At, B1); PG8_BAR;
;             PG8_LDA(At, 0, 1); PG8_STAGE(PG8_SA(0, 0), a2, voffA);
;             PG8_BAR; PG8_WAIT_L(0); PG8_MMA(1, 0, At, B0); PG8_BAR; PG8_SCHED;
;             PG8_STAGE(PG8_SB(0, 1), b2 + hstep, voffB);
;             PG8_WAIT_V(6); PG8_BAR; PG8_MMA(1, 1, At, B1); PG8_BAR;
;             PG8_LDB(B0, 1, 0); PG8_SCHED; PG8_LDA(At, 1, 0); PG8_STAGE(PG8_SA(0, 1), a2 + hstep, voffA);
;             PG8_WAIT_L(8); PG8_BAR; PG8_WAIT_L(0); PG8_MMA(0, 0, At, B0); PG8_BAR; PG8_SCHED;
;             PG8_LDB(B1, 1, 1); PG8_STAGE(PG8_SB(1, 0), b3, voffB);
;             PG8_BAR; PG8_WAIT_L(0); PG8_MMA(0, 1, At, B1); PG8_BAR;
;             PG8_LDA(At, 1, 1); PG8_STAGE(PG8_SA(1, 0), a3, voffA);
;             PG8_BAR; PG8_WAIT_L(0); PG8_MMA(1, 0, At, B0); PG8_BAR; PG8_SCHED;
;             PG8_STAGE(PG8_SB(1, 1), b3 + hstep, voffB);
;             PG8_WAIT_V(6); PG8_BAR; PG8_MMA(1, 1, At, B1); PG8_BAR;
	v_mfma_f32_16x16x32_bf16 v[60:63], v[108:111], v[144:147], 0
	v_mfma_f32_16x16x32_bf16 v[56:59], v[124:127], v[144:147], 0
	v_mfma_f32_16x16x32_bf16 v[44:47], v[108:111], v[152:155], 0
	v_mfma_f32_16x16x32_bf16 v[40:43], v[124:127], v[152:155], 0
	v_mfma_f32_16x16x32_bf16 v[28:31], v[108:111], v[160:163], 0
	v_mfma_f32_16x16x32_bf16 v[24:27], v[124:127], v[160:163], 0
	v_mfma_f32_16x16x32_bf16 v[12:15], v[108:111], v[168:171], 0
	v_mfma_f32_16x16x32_bf16 v[8:11], v[124:127], v[168:171], 0
	s_add_i32 s33, 0, 0x18000
	v_mfma_f32_16x16x32_bf16 v[60:63], v[112:115], v[148:151], v[60:63]
	v_mfma_f32_16x16x32_bf16 v[56:59], v[128:131], v[148:151], v[56:59]
	v_mfma_f32_16x16x32_bf16 v[44:47], v[112:115], v[156:159], v[44:47]
	v_mfma_f32_16x16x32_bf16 v[40:43], v[128:131], v[156:159], v[40:43]
	v_mfma_f32_16x16x32_bf16 v[28:31], v[112:115], v[164:167], v[28:31]
	v_mfma_f32_16x16x32_bf16 v[24:27], v[128:131], v[164:167], v[24:27]
	v_mfma_f32_16x16x32_bf16 v[12:15], v[112:115], v[172:175], v[12:15]
	v_mfma_f32_16x16x32_bf16 v[8:11], v[128:131], v[172:175], v[8:11]
	v_mfma_f32_16x16x32_bf16 v[52:55], v[188:191], v[144:147], 0
	v_mfma_f32_16x16x32_bf16 v[48:51], v[196:199], v[144:147], 0
	v_mfma_f32_16x16x32_bf16 v[36:39], v[188:191], v[152:155], 0
	v_mfma_f32_16x16x32_bf16 v[32:35], v[196:199], v[152:155], 0
	v_mfma_f32_16x16x32_bf16 v[20:23], v[188:191], v[160:163], 0
	v_mfma_f32_16x16x32_bf16 v[16:19], v[196:199], v[160:163], 0
	v_mfma_f32_16x16x32_bf16 v[4:7], v[188:191], v[168:171], 0
	v_mfma_f32_16x16x32_bf16 v[0:3], v[196:199], v[168:171], 0
	v_mfma_f32_16x16x32_bf16 v[52:55], v[192:195], v[148:151], v[52:55]
	v_mfma_f32_16x16x32_bf16 v[48:51], v[200:203], v[148:151], v[48:51]
	v_mfma_f32_16x16x32_bf16 v[36:39], v[192:195], v[156:159], v[36:39]
	v_mfma_f32_16x16x32_bf16 v[32:35], v[200:203], v[156:159], v[32:35]
	v_mfma_f32_16x16x32_bf16 v[20:23], v[192:195], v[164:167], v[20:23]
	v_mfma_f32_16x16x32_bf16 v[16:19], v[200:203], v[164:167], v[16:19]
	v_mfma_f32_16x16x32_bf16 v[4:7], v[192:195], v[172:175], v[4:7]
	v_mfma_f32_16x16x32_bf16 v[0:3], v[200:203], v[172:175], v[0:3]
	s_barrier
	s_setprio 0
	ds_read_b128 v[108:111], v247 offset:32768
	ds_read_b128 v[112:115], v247 offset:33792
	ds_read_b128 v[124:127], v247 offset:34816
	ds_read_b128 v[128:131], v247 offset:35840
	ds_read_b128 v[144:147], v248 offset:32768
	ds_read_b128 v[148:151], v248 offset:33792
	ds_read_b128 v[152:155], v248 offset:34816
	ds_read_b128 v[156:159], v248 offset:35840
	ds_read_b128 v[160:163], v248 offset:36864
	ds_read_b128 v[164:167], v248 offset:37888
	ds_read_b128 v[168:171], v248 offset:38912
	ds_read_b128 v[172:175], v248 offset:39936
	ds_read_b128 v[188:191], v249 offset:32768
	ds_read_b128 v[192:195], v249 offset:33792
	ds_read_b128 v[196:199], v249 offset:34816
	ds_read_b128 v[200:203], v249 offset:35840
	s_add_u32 s10, s30, 0x160000
	s_addc_u32 s11, s31, 0
	s_mov_b32 m0, s42
	v_lshl_add_u64 v[252:253], s[10:11], 0, v[176:177]
	global_load_lds_dwordx4 v[252:253], off
	v_lshl_add_u64 v[252:253], s[10:11], 0, v[180:181]
	s_mov_b32 m0, s43
	s_nop 0
	global_load_lds_dwordx4 v[252:253], off
	s_waitcnt vmcnt(8)
	s_waitcnt lgkmcnt(0)
	s_setprio 1
	s_barrier
	v_mfma_f32_16x16x32_bf16 v[140:143], v[108:111], v[144:147], v[140:143]
	v_mfma_f32_16x16x32_bf16 v[136:139], v[124:127], v[144:147], v[136:139]
	v_mfma_f32_16x16x32_bf16 v[116:119], v[108:111], v[152:155], v[116:119]
	v_mfma_f32_16x16x32_bf16 v[104:107], v[124:127], v[152:155], v[104:107]
	v_mfma_f32_16x16x32_bf16 v[92:95], v[108:111], v[160:163], v[92:95]
	v_mfma_f32_16x16x32_bf16 v[88:91], v[124:127], v[160:163], v[88:91]
	v_mfma_f32_16x16x32_bf16 v[76:79], v[108:111], v[168:171], v[76:79]
	v_mfma_f32_16x16x32_bf16 v[72:75], v[124:127], v[168:171], v[72:75]
	v_mfma_f32_16x16x32_bf16 v[140:143], v[112:115], v[148:151], v[140:143]
	v_mfma_f32_16x16x32_bf16 v[136:139], v[128:131], v[148:151], v[136:139]
	v_mfma_f32_16x16x32_bf16 v[116:119], v[112:115], v[156:159], v[116:119]
	v_mfma_f32_16x16x32_bf16 v[104:107], v[128:131], v[156:159], v[104:107]
	v_mfma_f32_16x16x32_bf16 v[92:95], v[112:115], v[164:167], v[92:95]
	v_mfma_f32_16x16x32_bf16 v[88:91], v[128:131], v[164:167], v[88:91]
	v_mfma_f32_16x16x32_bf16 v[76:79], v[112:115], v[172:175], v[76:79]
	v_mfma_f32_16x16x32_bf16 v[72:75], v[128:131], v[172:175], v[72:75]
	v_mfma_f32_16x16x32_bf16 v[132:135], v[188:191], v[144:147], v[132:135]
	v_mfma_f32_16x16x32_bf16 v[120:123], v[196:199], v[144:147], v[120:123]
	v_mfma_f32_16x16x32_bf16 v[100:103], v[188:191], v[152:155], v[100:103]
	v_mfma_f32_16x16x32_bf16 v[96:99], v[196:199], v[152:155], v[96:99]
	v_mfma_f32_16x16x32_bf16 v[84:87], v[188:191], v[160:163], v[84:87]
	v_mfma_f32_16x16x32_bf16 v[80:83], v[196:199], v[160:163], v[80:83]
	v_mfma_f32_16x16x32_bf16 v[68:71], v[188:191], v[168:171], v[68:71]
	v_mfma_f32_16x16x32_bf16 v[64:67], v[196:199], v[168:171], v[64:67]
	v_mfma_f32_16x16x32_bf16 v[132:135], v[192:195], v[148:151], v[132:135]
	v_mfma_f32_16x16x32_bf16 v[120:123], v[200:203], v[148:151], v[120:123]
	v_mfma_f32_16x16x32_bf16 v[100:103], v[192:195], v[156:159], v[100:103]
	v_mfma_f32_16x16x32_bf16 v[96:99], v[200:203], v[156:159], v[96:99]
	v_mfma_f32_16x16x32_bf16 v[84:87], v[192:195], v[164:167], v[84:87]
	v_mfma_f32_16x16x32_bf16 v[80:83], v[200:203], v[164:167], v[80:83]
	v_mfma_f32_16x16x32_bf16 v[68:71], v[192:195], v[172:175], v[68:71]
	v_mfma_f32_16x16x32_bf16 v[64:67], v[200:203], v[172:175], v[64:67]
	s_barrier
; #define PG8_STAGE(bufoff, gbase, voff) do { _Pragma("unroll") for (int _i = 0; _i < 2; ++_i) \
;         __builtin_amdgcn_global_load_lds((const unsigned*)((const char*)(gbase) + (voff)[_i]), (PG8_LAS unsigned*)(lds + (bufoff) + ldsw + _i * 8192), 16, 0, 0); } while (0)
; #define PG8_LDA(dst, b, h) do { _Pragma("unroll") for (int m = 0; m < 4; ++m) _Pragma("unroll") for (int k = 0; k < 2; ++k) dst[m][k] = *(const PG8_LAS bf16x8*)(lds + PG8_SA(b, h) + aoff + m * 2048 + k * 1024); } while (0)
; #define PG8_LDB(dst, b, h) do { _Pragma("unroll") for (int n = 0; n < 2; ++n) _Pragma("unroll") for (int k = 0; k < 2; ++k) dst[n][k] = *(const PG8_LAS bf16x8*)(lds + PG8_SB(b, h) + boff + n * 2048 + k * 1024); } while (0)
; #define PG8_WAIT_V(n) asm volatile("s_waitcnt vmcnt(" #n ")" ::: "memory")
; #define PG8_WAIT_L(n) asm volatile("s_waitcnt lgkmcnt(" #n ")" ::: "memory")
; #define PG8_BAR __builtin_amdgcn_s_barrier()
; #define PG8_SCHED __builtin_amdgcn_sched_barrier(0)
; template <class Epi, class Sched>
; __device__ __forceinline__ void gemm_phase(PG8_LAS unsigned char* lds, const Gemm g, const Sched& S, const Epi& E) {
;     ...
;             PG8_LDB(B0, 0, 0); PG8_SCHED; PG8_LDA(At, 0, 0); PG8_STAGE(PG8_SA(1, 1), a1 + hstep, voffA);
;             PG8_WAIT_L(8); PG8_BAR; PG8_WAIT_L(0); PG8_MMA(0, 0, At, B0); PG8_BAR; PG8_SCHED;
;             PG8_LDB(B1, 0, 1); PG8_STAGE(PG8_SB(0, 0), b2, voffB);
;             PG8_BAR; PG8_WAIT_L(0); PG8_MMA(0, 1, At, B1); PG8_BAR;
;             PG8_LDA(At, 0, 1); PG8_STAGE(PG8_SA(0, 0), a2, voffA);
;             PG8_BAR; PG8_WAIT_L(0); PG8_MMA(1, 0, At, B0); PG8_BAR; PG8_SCHED;
;             PG8_STAGE(PG8_SB(0, 1), b2 + hstep, voffB);
;             PG8_WAIT_V(6); PG8_BAR; PG8_MMA(1, 1, At, B1); PG8_BAR;
;             PG8_LDB(B0, 1, 0); PG8_SCHED; PG8_LDA(At, 1, 0); PG8_STAGE(PG8_SA(0, 1), a2 + hstep, voffA);
;             PG8_WAIT_L(8); PG8_BAR; PG8_WAIT_L(0); PG8_MMA(0, 0, At, B0); PG8_BAR; PG8_SCHED;
;             PG8_LDB(B1, 1, 1); PG8_STAGE(PG8_SB(1, 0), b3, voffB);
;             PG8_BAR; PG8_WAIT_L(0); PG8_MMA(0, 1, At, B1); PG8_BAR;
;             PG8_LDA(At, 1, 1); PG8_STAGE(PG8_SA(1, 0), a3, voffA);
;             PG8_BAR; PG8_WAIT_L(0); PG8_MMA(1, 0, At, B0); PG8_BAR; PG8_SCHED;
;             PG8_STAGE(PG8_SB(1, 1), b3 + hstep, voffB);
;             PG8_WAIT_V(6); PG8_BAR; PG8_MMA(1, 1, At, B1); PG8_BAR;
;         }
	s_setprio 0
	ds_read_b128 v[144:147], v248 offset:49152
	ds_read_b128 v[148:151], v248 offset:50176
	ds_read_b128 v[152:155], v248 offset:51200
	ds_read_b128 v[156:159], v248 offset:52224
	ds_read_b128 v[160:163], v248 offset:53248
	ds_read_b128 v[164:167], v248 offset:54272
	ds_read_b128 v[168:171], v248 offset:55296
	ds_read_b128 v[172:175], v248 offset:56320
	s_add_i32 s30, 0, 0x1c000
	s_add_i32 s10, s33, s39
	v_lshl_add_u64 v[204:205], v[204:205], 0, s[18:19]
	s_mov_b32 m0, s10
	s_nop 0
	global_load_lds_dwordx4 v[204:205], off
	v_lshl_add_u64 v[204:205], v[206:207], 0, s[18:19]
	s_add_i32 m0, s10, 0x2000
	s_nop 0
	global_load_lds_dwordx4 v[204:205], off
	s_mov_b32 m0, s45
	v_lshl_add_u64 v[204:205], v[208:209], 0, s[18:19]
	global_load_lds_dwordx4 v[204:205], off
	v_lshl_add_u64 v[204:205], v[210:211], 0, s[18:19]
	s_mov_b32 m0, s46
	s_nop 0
	global_load_lds_dwordx4 v[204:205], off
	s_add_u32 s10, s28, 0x160080
	s_addc_u32 s11, s29, 0
	s_add_i32 s28, s30, s39
	v_lshl_add_u64 v[252:253], s[10:11], 0, v[178:179]
	s_mov_b32 m0, s28
	s_nop 0
	global_load_lds_dwordx4 v[252:253], off
	v_lshl_add_u64 v[252:253], s[10:11], 0, v[182:183]
	s_add_i32 m0, s28, 0x2000
	s_nop 0
	global_load_lds_dwordx4 v[252:253], off
	s_waitcnt vmcnt(8)
	s_waitcnt lgkmcnt(0)
	s_setprio 1
	s_barrier
	v_mfma_f32_16x16x32_bf16 v[60:63], v[108:111], v[144:147], v[60:63]
	v_mfma_f32_16x16x32_bf16 v[56:59], v[124:127], v[144:147], v[56:59]
	v_mfma_f32_16x16x32_bf16 v[44:47], v[108:111], v[152:155], v[44:47]
	v_mfma_f32_16x16x32_bf16 v[40:43], v[124:127], v[152:155], v[40:43]
	v_mfma_f32_16x16x32_bf16 v[28:31], v[108:111], v[160:163], v[28:31]
	v_mfma_f32_16x16x32_bf16 v[24:27], v[124:127], v[160:163], v[24:27]
	v_mfma_f32_16x16x32_bf16 v[12:15], v[108:111], v[168:171], v[12:15]
	v_mfma_f32_16x16x32_bf16 v[8:11], v[124:127], v[168:171], v[8:11]
	s_add_i32 s69, s69, 2
	s_add_u32 s26, s26, 0x100
	s_addc_u32 s27, s27, 0
	s_add_u32 s67, s67, 0x100
	s_addc_u32 s68, s68, 0
	s_cmpk_gt_u32 s69, 0x55
	v_mfma_f32_16x16x32_bf16 v[60:63], v[112:115], v[148:151], v[60:63]
	v_mfma_f32_16x16x32_bf16 v[56:59], v[128:131], v[148:151], v[56:59]
	v_mfma_f32_16x16x32_bf16 v[44:47], v[112:115], v[156:159], v[44:47]
	v_mfma_f32_16x16x32_bf16 v[40:43], v[128:131], v[156:159], v[40:43]
	v_mfma_f32_16x16x32_bf16 v[28:31], v[112:115], v[164:167], v[28:31]
	v_mfma_f32_16x16x32_bf16 v[24:27], v[128:131], v[164:167], v[24:27]
	v_mfma_f32_16x16x32_bf16 v[12:15], v[112:115], v[172:175], v[12:15]
	v_mfma_f32_16x16x32_bf16 v[8:11], v[128:131], v[172:175], v[8:11]
	v_mfma_f32_16x16x32_bf16 v[52:55], v[188:191], v[144:147], v[52:55]
	v_mfma_f32_16x16x32_bf16 v[48:51], v[196:199], v[144:147], v[48:51]
	v_mfma_f32_16x16x32_bf16 v[36:39], v[188:191], v[152:155], v[36:39]
	v_mfma_f32_16x16x32_bf16 v[32:35], v[196:199], v[152:155], v[32:35]
	v_mfma_f32_16x16x32_bf16 v[20:23], v[188:191], v[160:163], v[20:23]
	v_mfma_f32_16x16x32_bf16 v[16:19], v[196:199], v[160:163], v[16:19]
	v_mfma_f32_16x16x32_bf16 v[4:7], v[188:191], v[168:171], v[4:7]
	v_mfma_f32_16x16x32_bf16 v[0:3], v[196:199], v[168:171], v[0:3]
	v_mfma_f32_16x16x32_bf16 v[52:55], v[192:195], v[148:151], v[52:55]
	v_mfma_f32_16x16x32_bf16 v[48:51], v[200:203], v[148:151], v[48:51]
	v_mfma_f32_16x16x32_bf16 v[36:39], v[192:195], v[156:159], v[36:39]
	v_mfma_f32_16x16x32_bf16 v[32:35], v[200:203], v[156:159], v[32:35]
	v_mfma_f32_16x16x32_bf16 v[20:23], v[192:195], v[164:167], v[20:23]
	v_mfma_f32_16x16x32_bf16 v[16:19], v[200:203], v[164:167], v[16:19]
	v_mfma_f32_16x16x32_bf16 v[4:7], v[192:195], v[172:175], v[4:7]
	v_mfma_f32_16x16x32_bf16 v[0:3], v[200:203], v[172:175], v[0:3]
	s_barrier
